# additionally s_setprio 0 moved after the closing barrier of each MFMA block (off the arrival path), 24 sites
# baseline (speedup 1.0000x reference)
.LBB0_180:
	s_add_u32 s12, s26, s8
	s_addc_u32 s13, s27, s9
	s_add_u32 s12, s12, 0x100
	s_addc_u32 s13, s13, 0
	s_add_u32 s81, s67, s8
	s_addc_u32 s83, s43, s9
	s_add_i32 s95, 0, 0x10000
	s_cmpk_eq_i32 s8, 0xf00
	s_cselect_b32 s35, s25, s13
	s_cselect_b32 s34, s36, s12
	s_cselect_b32 s13, s23, s83
	s_cselect_b32 s12, s37, s81
	s_add_i32 s81, 0, 0x14000
	v_add_u32_e32 v148, s95, v230
	v_add_u32_e32 v164, s81, v230
	ds_read_b128 v[136:139], v148
	ds_read_b128 v[140:143], v148 offset:1024
	ds_read_b128 v[144:147], v148 offset:2048
	ds_read_b128 v[148:151], v148 offset:3072
	ds_read_b128 v[152:155], v164
	ds_read_b128 v[156:159], v164 offset:1024
	ds_read_b128 v[160:163], v164 offset:2048
	ds_read_b128 v[164:167], v164 offset:3072
	v_lshl_add_u64 v[196:197], v[132:133], 0, s[8:9]
	s_add_i32 m0, s39, 0xc000
	ds_read_b128 v[168:171], v242
	ds_read_b128 v[188:191], v242 offset:1024
	ds_read_b128 v[192:195], v242 offset:2048
	ds_read_b128 v[204:207], v242 offset:3072
	ds_read_b128 v[208:211], v242 offset:4096
	ds_read_b128 v[212:215], v242 offset:5120
	ds_read_b128 v[244:247], v242 offset:6144
	ds_read_b128 v[248:251], v242 offset:7168
	global_load_lds_dwordx4 v[196:197], off
	v_lshl_add_u64 v[196:197], v[134:135], 0, s[8:9]
	s_add_i32 m0, s39, 0xe000
	s_nop 0
	global_load_lds_dwordx4 v[196:197], off
	s_waitcnt vmcnt(8)
	s_waitcnt lgkmcnt(0)
	s_setprio 1
	s_barrier
	v_mfma_f32_16x16x32_bf16 v[8:11], v[136:139], v[168:171], v[8:11]
	v_mfma_f32_16x16x32_bf16 v[128:131], v[144:147], v[168:171], v[128:131]
	v_mfma_f32_16x16x32_bf16 v[124:127], v[136:139], v[192:195], v[124:127]
	v_mfma_f32_16x16x32_bf16 v[120:123], v[144:147], v[192:195], v[120:123]
	v_mfma_f32_16x16x32_bf16 v[116:119], v[136:139], v[208:211], v[116:119]
	v_mfma_f32_16x16x32_bf16 v[112:115], v[144:147], v[208:211], v[112:115]
	v_mfma_f32_16x16x32_bf16 v[108:111], v[136:139], v[244:247], v[108:111]
	v_mfma_f32_16x16x32_bf16 v[104:107], v[144:147], v[244:247], v[104:107]
	v_mfma_f32_16x16x32_bf16 v[8:11], v[140:143], v[188:191], v[8:11]
	v_mfma_f32_16x16x32_bf16 v[128:131], v[148:151], v[188:191], v[128:131]
	v_mfma_f32_16x16x32_bf16 v[124:127], v[140:143], v[204:207], v[124:127]
	v_mfma_f32_16x16x32_bf16 v[120:123], v[148:151], v[204:207], v[120:123]
	v_mfma_f32_16x16x32_bf16 v[116:119], v[140:143], v[212:215], v[116:119]
	v_mfma_f32_16x16x32_bf16 v[112:115], v[148:151], v[212:215], v[112:115]
	v_mfma_f32_16x16x32_bf16 v[108:111], v[140:143], v[248:251], v[108:111]
	v_mfma_f32_16x16x32_bf16 v[104:107], v[148:151], v[248:251], v[104:107]
	s_setprio 0
	s_setprio 1
	v_mfma_f32_16x16x32_bf16 v[100:103], v[152:155], v[168:171], v[100:103]
	v_mfma_f32_16x16x32_bf16 v[96:99], v[160:163], v[168:171], v[96:99]
	v_mfma_f32_16x16x32_bf16 v[92:95], v[152:155], v[192:195], v[92:95]
	v_mfma_f32_16x16x32_bf16 v[88:91], v[160:163], v[192:195], v[88:91]
	v_mfma_f32_16x16x32_bf16 v[84:87], v[152:155], v[208:211], v[84:87]
	v_mfma_f32_16x16x32_bf16 v[80:83], v[160:163], v[208:211], v[80:83]
	v_mfma_f32_16x16x32_bf16 v[76:79], v[152:155], v[244:247], v[76:79]
	v_mfma_f32_16x16x32_bf16 v[72:75], v[160:163], v[244:247], v[72:75]
	v_mfma_f32_16x16x32_bf16 v[100:103], v[156:159], v[188:191], v[100:103]
	v_mfma_f32_16x16x32_bf16 v[96:99], v[164:167], v[188:191], v[96:99]
	v_mfma_f32_16x16x32_bf16 v[92:95], v[156:159], v[204:207], v[92:95]
	v_mfma_f32_16x16x32_bf16 v[88:91], v[164:167], v[204:207], v[88:91]
	v_mfma_f32_16x16x32_bf16 v[84:87], v[156:159], v[212:215], v[84:87]
	v_mfma_f32_16x16x32_bf16 v[80:83], v[164:167], v[212:215], v[80:83]
	v_mfma_f32_16x16x32_bf16 v[76:79], v[156:159], v[248:251], v[76:79]
	v_mfma_f32_16x16x32_bf16 v[72:75], v[164:167], v[248:251], v[72:75]
	s_barrier
	s_setprio 0
	s_add_i32 s83, s95, s38
	v_lshl_add_u64 v[196:197], s[12:13], 0, v[172:173]
	s_mov_b32 m0, s83
	ds_read_b128 v[168:171], v242 offset:16384
	ds_read_b128 v[188:191], v242 offset:17408
	ds_read_b128 v[192:195], v242 offset:18432
	ds_read_b128 v[204:207], v242 offset:19456
	ds_read_b128 v[208:211], v242 offset:20480
	ds_read_b128 v[212:215], v242 offset:21504
	ds_read_b128 v[244:247], v242 offset:22528
	ds_read_b128 v[248:251], v242 offset:23552
	global_load_lds_dwordx4 v[196:197], off
	s_add_i32 m0, s83, 0x2000
	s_add_u32 vcc_lo, s12, 0x80000
	v_lshl_add_u64 v[198:199], s[12:13], 0, v[176:177]
	s_addc_u32 vcc_hi, s13, 0
	s_add_i32 s81, s81, s38
	global_load_lds_dwordx4 v[198:199], off
	v_lshl_add_u64 v[200:201], vcc, 0, v[172:173]
	s_mov_b32 m0, s81
	v_lshl_add_u64 v[202:203], s[34:35], 0, v[174:175]
	global_load_lds_dwordx4 v[200:201], off
	v_lshl_add_u64 v[200:201], vcc, 0, v[176:177]
	s_add_i32 m0, s81, 0x2000
	s_nop 0
	global_load_lds_dwordx4 v[200:201], off
	v_lshl_add_u64 v[200:201], s[34:35], 0, v[0:1]
	s_mov_b32 m0, s39
	s_nop 0
	global_load_lds_dwordx4 v[200:201], off
	s_mov_b32 m0, s46
	s_nop 0
	global_load_lds_dwordx4 v[202:203], off
	s_waitcnt vmcnt(8)
	s_waitcnt lgkmcnt(0)
	s_setprio 1
	s_barrier
	v_mfma_f32_16x16x32_bf16 v[68:71], v[136:139], v[168:171], v[68:71]
	v_mfma_f32_16x16x32_bf16 v[64:67], v[144:147], v[168:171], v[64:67]
	v_mfma_f32_16x16x32_bf16 v[60:63], v[136:139], v[192:195], v[60:63]
	v_mfma_f32_16x16x32_bf16 v[56:59], v[144:147], v[192:195], v[56:59]
	v_mfma_f32_16x16x32_bf16 v[52:55], v[136:139], v[208:211], v[52:55]
	v_mfma_f32_16x16x32_bf16 v[48:51], v[144:147], v[208:211], v[48:51]
	v_mfma_f32_16x16x32_bf16 v[44:47], v[136:139], v[244:247], v[44:47]
	v_mfma_f32_16x16x32_bf16 v[40:43], v[144:147], v[244:247], v[40:43]
	v_mfma_f32_16x16x32_bf16 v[68:71], v[140:143], v[188:191], v[68:71]
	v_mfma_f32_16x16x32_bf16 v[64:67], v[148:151], v[188:191], v[64:67]
	v_mfma_f32_16x16x32_bf16 v[60:63], v[140:143], v[204:207], v[60:63]
	v_mfma_f32_16x16x32_bf16 v[56:59], v[148:151], v[204:207], v[56:59]
	v_mfma_f32_16x16x32_bf16 v[52:55], v[140:143], v[212:215], v[52:55]
	v_mfma_f32_16x16x32_bf16 v[48:51], v[148:151], v[212:215], v[48:51]
	v_mfma_f32_16x16x32_bf16 v[44:47], v[140:143], v[248:251], v[44:47]
	v_mfma_f32_16x16x32_bf16 v[40:43], v[148:151], v[248:251], v[40:43]
	s_setprio 0
	s_setprio 1
	v_mfma_f32_16x16x32_bf16 v[36:39], v[152:155], v[168:171], v[36:39]
	v_mfma_f32_16x16x32_bf16 v[32:35], v[160:163], v[168:171], v[32:35]
	v_mfma_f32_16x16x32_bf16 v[28:31], v[152:155], v[192:195], v[28:31]
	v_mfma_f32_16x16x32_bf16 v[24:27], v[160:163], v[192:195], v[24:27]
	v_mfma_f32_16x16x32_bf16 v[20:23], v[152:155], v[208:211], v[20:23]
	v_mfma_f32_16x16x32_bf16 v[16:19], v[160:163], v[208:211], v[16:19]
	v_mfma_f32_16x16x32_bf16 v[12:15], v[152:155], v[244:247], v[12:15]
	v_mfma_f32_16x16x32_bf16 v[4:7], v[160:163], v[244:247], v[4:7]
	v_mfma_f32_16x16x32_bf16 v[36:39], v[156:159], v[188:191], v[36:39]
	v_mfma_f32_16x16x32_bf16 v[32:35], v[164:167], v[188:191], v[32:35]
	v_mfma_f32_16x16x32_bf16 v[28:31], v[156:159], v[204:207], v[28:31]
	v_mfma_f32_16x16x32_bf16 v[24:27], v[164:167], v[204:207], v[24:27]
	v_mfma_f32_16x16x32_bf16 v[20:23], v[156:159], v[212:215], v[20:23]
	v_mfma_f32_16x16x32_bf16 v[16:19], v[164:167], v[212:215], v[16:19]
	v_mfma_f32_16x16x32_bf16 v[12:15], v[156:159], v[248:251], v[12:15]
	v_mfma_f32_16x16x32_bf16 v[4:7], v[164:167], v[248:251], v[4:7]
	s_barrier
	s_setprio 0
	s_add_i32 s81, 0, 0x18000
	s_add_i32 s83, 0, 0x1c000
	v_add_u32_e32 v148, s81, v230
	v_add_u32_e32 v164, s83, v230
	ds_read_b128 v[136:139], v148
	ds_read_b128 v[140:143], v148 offset:1024
	ds_read_b128 v[144:147], v148 offset:2048
	ds_read_b128 v[148:151], v148 offset:3072
	ds_read_b128 v[152:155], v164
	ds_read_b128 v[156:159], v164 offset:1024
	ds_read_b128 v[160:163], v164 offset:2048
	ds_read_b128 v[164:167], v164 offset:3072
	s_add_u32 s34, s34, 0x80000
	s_addc_u32 s35, s35, 0
	s_mov_b32 m0, s47
	v_lshl_add_u64 v[216:217], s[34:35], 0, v[0:1]
	ds_read_b128 v[168:171], v242 offset:32768
	ds_read_b128 v[188:191], v242 offset:33792
	ds_read_b128 v[192:195], v242 offset:34816
	ds_read_b128 v[204:207], v242 offset:35840
	ds_read_b128 v[208:211], v242 offset:36864
	ds_read_b128 v[212:215], v242 offset:37888
	ds_read_b128 v[244:247], v242 offset:38912
	ds_read_b128 v[248:251], v242 offset:39936
	global_load_lds_dwordx4 v[216:217], off
	v_lshl_add_u64 v[216:217], s[34:35], 0, v[174:175]
	s_mov_b32 m0, s51
	s_nop 0
	global_load_lds_dwordx4 v[216:217], off
	s_waitcnt vmcnt(8)
	s_waitcnt lgkmcnt(0)
	s_setprio 1
	s_barrier
	v_mfma_f32_16x16x32_bf16 v[8:11], v[136:139], v[168:171], v[8:11]
	v_mfma_f32_16x16x32_bf16 v[128:131], v[144:147], v[168:171], v[128:131]
	v_mfma_f32_16x16x32_bf16 v[124:127], v[136:139], v[192:195], v[124:127]
	v_mfma_f32_16x16x32_bf16 v[120:123], v[144:147], v[192:195], v[120:123]
	v_mfma_f32_16x16x32_bf16 v[116:119], v[136:139], v[208:211], v[116:119]
	v_mfma_f32_16x16x32_bf16 v[112:115], v[144:147], v[208:211], v[112:115]
	v_mfma_f32_16x16x32_bf16 v[108:111], v[136:139], v[244:247], v[108:111]
	v_mfma_f32_16x16x32_bf16 v[104:107], v[144:147], v[244:247], v[104:107]
	v_mfma_f32_16x16x32_bf16 v[8:11], v[140:143], v[188:191], v[8:11]
	v_mfma_f32_16x16x32_bf16 v[128:131], v[148:151], v[188:191], v[128:131]
	v_mfma_f32_16x16x32_bf16 v[124:127], v[140:143], v[204:207], v[124:127]
	v_mfma_f32_16x16x32_bf16 v[120:123], v[148:151], v[204:207], v[120:123]
	v_mfma_f32_16x16x32_bf16 v[116:119], v[140:143], v[212:215], v[116:119]
	v_mfma_f32_16x16x32_bf16 v[112:115], v[148:151], v[212:215], v[112:115]
	v_mfma_f32_16x16x32_bf16 v[108:111], v[140:143], v[248:251], v[108:111]
	v_mfma_f32_16x16x32_bf16 v[104:107], v[148:151], v[248:251], v[104:107]
	s_setprio 0
	s_setprio 1
	v_mfma_f32_16x16x32_bf16 v[100:103], v[152:155], v[168:171], v[100:103]
	v_mfma_f32_16x16x32_bf16 v[96:99], v[160:163], v[168:171], v[96:99]
	v_mfma_f32_16x16x32_bf16 v[92:95], v[152:155], v[192:195], v[92:95]
	v_mfma_f32_16x16x32_bf16 v[88:91], v[160:163], v[192:195], v[88:91]
	v_mfma_f32_16x16x32_bf16 v[84:87], v[152:155], v[208:211], v[84:87]
	v_mfma_f32_16x16x32_bf16 v[80:83], v[160:163], v[208:211], v[80:83]
	v_mfma_f32_16x16x32_bf16 v[76:79], v[152:155], v[244:247], v[76:79]
	v_mfma_f32_16x16x32_bf16 v[72:75], v[160:163], v[244:247], v[72:75]
	v_mfma_f32_16x16x32_bf16 v[100:103], v[156:159], v[188:191], v[100:103]
	v_mfma_f32_16x16x32_bf16 v[96:99], v[164:167], v[188:191], v[96:99]
	v_mfma_f32_16x16x32_bf16 v[92:95], v[156:159], v[204:207], v[92:95]
	v_mfma_f32_16x16x32_bf16 v[88:91], v[164:167], v[204:207], v[88:91]
	v_mfma_f32_16x16x32_bf16 v[84:87], v[156:159], v[212:215], v[84:87]
	v_mfma_f32_16x16x32_bf16 v[80:83], v[164:167], v[212:215], v[80:83]
	v_mfma_f32_16x16x32_bf16 v[76:79], v[156:159], v[248:251], v[76:79]
	v_mfma_f32_16x16x32_bf16 v[72:75], v[164:167], v[248:251], v[72:75]
	s_barrier
	s_setprio 0
	s_add_i32 s34, s81, s38
	v_lshl_add_u64 v[196:197], v[196:197], 0, s[70:71]
	s_mov_b32 m0, s34
	ds_read_b128 v[168:171], v242 offset:49152
	ds_read_b128 v[188:191], v242 offset:50176
	ds_read_b128 v[192:195], v242 offset:51200
	ds_read_b128 v[204:207], v242 offset:52224
	ds_read_b128 v[208:211], v242 offset:53248
	ds_read_b128 v[212:215], v242 offset:54272
	ds_read_b128 v[244:247], v242 offset:55296
	ds_read_b128 v[248:251], v242 offset:56320
	global_load_lds_dwordx4 v[196:197], off
	s_add_i32 m0, s34, 0x2000
	s_add_u32 s12, s12, 0x80080
	v_lshl_add_u64 v[196:197], v[198:199], 0, s[70:71]
	s_addc_u32 s13, s13, 0
	s_add_i32 s34, s83, s38
	global_load_lds_dwordx4 v[196:197], off
	v_lshl_add_u64 v[196:197], s[12:13], 0, v[172:173]
	s_mov_b32 m0, s34
	s_nop 0
	global_load_lds_dwordx4 v[196:197], off
	v_lshl_add_u64 v[196:197], s[12:13], 0, v[176:177]
	s_add_i32 m0, s34, 0x2000
	s_nop 0
	global_load_lds_dwordx4 v[196:197], off
	v_lshl_add_u64 v[196:197], v[200:201], 0, s[70:71]
	s_mov_b32 m0, s74
	s_nop 0
	global_load_lds_dwordx4 v[196:197], off
	v_lshl_add_u64 v[196:197], v[202:203], 0, s[70:71]
	s_mov_b32 m0, s75
	s_nop 0
	global_load_lds_dwordx4 v[196:197], off
	s_waitcnt vmcnt(8)
	s_waitcnt lgkmcnt(0)
	s_setprio 1
	s_barrier
	v_mfma_f32_16x16x32_bf16 v[68:71], v[136:139], v[168:171], v[68:71]
	v_mfma_f32_16x16x32_bf16 v[64:67], v[144:147], v[168:171], v[64:67]
	v_mfma_f32_16x16x32_bf16 v[60:63], v[136:139], v[192:195], v[60:63]
	v_mfma_f32_16x16x32_bf16 v[56:59], v[144:147], v[192:195], v[56:59]
	v_mfma_f32_16x16x32_bf16 v[52:55], v[136:139], v[208:211], v[52:55]
	v_mfma_f32_16x16x32_bf16 v[48:51], v[144:147], v[208:211], v[48:51]
	v_mfma_f32_16x16x32_bf16 v[44:47], v[136:139], v[244:247], v[44:47]
	v_mfma_f32_16x16x32_bf16 v[40:43], v[144:147], v[244:247], v[40:43]
	v_mfma_f32_16x16x32_bf16 v[68:71], v[140:143], v[188:191], v[68:71]
	v_mfma_f32_16x16x32_bf16 v[64:67], v[148:151], v[188:191], v[64:67]
	v_mfma_f32_16x16x32_bf16 v[60:63], v[140:143], v[204:207], v[60:63]
	v_mfma_f32_16x16x32_bf16 v[56:59], v[148:151], v[204:207], v[56:59]
	v_mfma_f32_16x16x32_bf16 v[52:55], v[140:143], v[212:215], v[52:55]
	v_mfma_f32_16x16x32_bf16 v[48:51], v[148:151], v[212:215], v[48:51]
	v_mfma_f32_16x16x32_bf16 v[44:47], v[140:143], v[248:251], v[44:47]
	v_mfma_f32_16x16x32_bf16 v[40:43], v[148:151], v[248:251], v[40:43]
	s_setprio 0
	s_setprio 1
	v_mfma_f32_16x16x32_bf16 v[36:39], v[152:155], v[168:171], v[36:39]
	v_mfma_f32_16x16x32_bf16 v[32:35], v[160:163], v[168:171], v[32:35]
	v_mfma_f32_16x16x32_bf16 v[28:31], v[152:155], v[192:195], v[28:31]
	v_mfma_f32_16x16x32_bf16 v[24:27], v[160:163], v[192:195], v[24:27]
	v_mfma_f32_16x16x32_bf16 v[20:23], v[152:155], v[208:211], v[20:23]
	v_mfma_f32_16x16x32_bf16 v[16:19], v[160:163], v[208:211], v[16:19]
	v_mfma_f32_16x16x32_bf16 v[12:15], v[152:155], v[244:247], v[12:15]
	v_mfma_f32_16x16x32_bf16 v[4:7], v[160:163], v[244:247], v[4:7]
	v_mfma_f32_16x16x32_bf16 v[36:39], v[156:159], v[188:191], v[36:39]
	v_mfma_f32_16x16x32_bf16 v[32:35], v[164:167], v[188:191], v[32:35]
	v_mfma_f32_16x16x32_bf16 v[28:31], v[156:159], v[204:207], v[28:31]
	v_mfma_f32_16x16x32_bf16 v[24:27], v[164:167], v[204:207], v[24:27]
	v_mfma_f32_16x16x32_bf16 v[20:23], v[156:159], v[212:215], v[20:23]
	v_mfma_f32_16x16x32_bf16 v[16:19], v[164:167], v[212:215], v[16:19]
	v_mfma_f32_16x16x32_bf16 v[12:15], v[156:159], v[248:251], v[12:15]
	v_mfma_f32_16x16x32_bf16 v[4:7], v[164:167], v[248:251], v[4:7]
	s_barrier
	s_setprio 0
	s_add_i32 s42, s42, 2
	s_add_u32 s8, s8, 0x100
	s_addc_u32 s9, s9, 0
	s_cmp_gt_u32 s42, 29
	s_cbranch_scc0 .LBB0_180
	s_and_b64 vcc, exec, s[20:21]
	s_cbranch_vccz .LBB0_183
	s_barrier

.LBB0_319:
	s_add_u32 s12, s28, s8
	s_addc_u32 s13, s29, s9
	s_add_u32 s12, s12, 0x100
	s_addc_u32 s13, s13, 0
	s_add_u32 s43, s92, s8
	s_addc_u32 s66, s93, s9
	s_add_i32 s67, 0, 0x10000
	s_cmpk_eq_i32 s8, 0xf00
	s_cselect_b32 s17, s27, s13
	s_cselect_b32 s16, s36, s12
	s_cselect_b32 s13, s25, s66
	s_cselect_b32 s12, s37, s43
	s_add_i32 s43, 0, 0x14000
	v_add_u32_e32 v148, s67, v229
	v_add_u32_e32 v164, s43, v229
	ds_read_b128 v[136:139], v148
	ds_read_b128 v[140:143], v148 offset:1024
	ds_read_b128 v[144:147], v148 offset:2048
	ds_read_b128 v[148:151], v148 offset:3072
	ds_read_b128 v[152:155], v164
	ds_read_b128 v[156:159], v164 offset:1024
	ds_read_b128 v[160:163], v164 offset:2048
	ds_read_b128 v[164:167], v164 offset:3072
	v_lshl_add_u64 v[194:195], v[132:133], 0, s[8:9]
	s_add_i32 m0, s39, 0xc000
	ds_read_b128 v[168:171], v242
	ds_read_b128 v[186:189], v242 offset:1024
	ds_read_b128 v[190:193], v242 offset:2048
	ds_read_b128 v[204:207], v242 offset:3072
	ds_read_b128 v[208:211], v242 offset:4096
	ds_read_b128 v[212:215], v242 offset:5120
	ds_read_b128 v[244:247], v242 offset:6144
	ds_read_b128 v[248:251], v242 offset:7168
	global_load_lds_dwordx4 v[194:195], off
	v_lshl_add_u64 v[194:195], v[134:135], 0, s[8:9]
	s_add_i32 m0, s39, 0xe000
	s_nop 0
	global_load_lds_dwordx4 v[194:195], off
	s_waitcnt vmcnt(8)
	s_waitcnt lgkmcnt(0)
	s_setprio 1
	s_barrier
	v_mfma_f32_16x16x32_bf16 v[8:11], v[136:139], v[168:171], v[8:11]
	v_mfma_f32_16x16x32_bf16 v[128:131], v[144:147], v[168:171], v[128:131]
	v_mfma_f32_16x16x32_bf16 v[124:127], v[136:139], v[190:193], v[124:127]
	v_mfma_f32_16x16x32_bf16 v[120:123], v[144:147], v[190:193], v[120:123]
	v_mfma_f32_16x16x32_bf16 v[116:119], v[136:139], v[208:211], v[116:119]
	v_mfma_f32_16x16x32_bf16 v[112:115], v[144:147], v[208:211], v[112:115]
	v_mfma_f32_16x16x32_bf16 v[108:111], v[136:139], v[244:247], v[108:111]
	v_mfma_f32_16x16x32_bf16 v[104:107], v[144:147], v[244:247], v[104:107]
	v_mfma_f32_16x16x32_bf16 v[8:11], v[140:143], v[186:189], v[8:11]
	v_mfma_f32_16x16x32_bf16 v[128:131], v[148:151], v[186:189], v[128:131]
	v_mfma_f32_16x16x32_bf16 v[124:127], v[140:143], v[204:207], v[124:127]
	v_mfma_f32_16x16x32_bf16 v[120:123], v[148:151], v[204:207], v[120:123]
	v_mfma_f32_16x16x32_bf16 v[116:119], v[140:143], v[212:215], v[116:119]
	v_mfma_f32_16x16x32_bf16 v[112:115], v[148:151], v[212:215], v[112:115]
	v_mfma_f32_16x16x32_bf16 v[108:111], v[140:143], v[248:251], v[108:111]
	v_mfma_f32_16x16x32_bf16 v[104:107], v[148:151], v[248:251], v[104:107]
	s_setprio 0
	s_setprio 1
	v_mfma_f32_16x16x32_bf16 v[100:103], v[152:155], v[168:171], v[100:103]
	v_mfma_f32_16x16x32_bf16 v[96:99], v[160:163], v[168:171], v[96:99]
	v_mfma_f32_16x16x32_bf16 v[92:95], v[152:155], v[190:193], v[92:95]
	v_mfma_f32_16x16x32_bf16 v[88:91], v[160:163], v[190:193], v[88:91]
	v_mfma_f32_16x16x32_bf16 v[84:87], v[152:155], v[208:211], v[84:87]
	v_mfma_f32_16x16x32_bf16 v[80:83], v[160:163], v[208:211], v[80:83]
	v_mfma_f32_16x16x32_bf16 v[76:79], v[152:155], v[244:247], v[76:79]
	v_mfma_f32_16x16x32_bf16 v[72:75], v[160:163], v[244:247], v[72:75]
	v_mfma_f32_16x16x32_bf16 v[100:103], v[156:159], v[186:189], v[100:103]
	v_mfma_f32_16x16x32_bf16 v[96:99], v[164:167], v[186:189], v[96:99]
	v_mfma_f32_16x16x32_bf16 v[92:95], v[156:159], v[204:207], v[92:95]
	v_mfma_f32_16x16x32_bf16 v[88:91], v[164:167], v[204:207], v[88:91]
	v_mfma_f32_16x16x32_bf16 v[84:87], v[156:159], v[212:215], v[84:87]
	v_mfma_f32_16x16x32_bf16 v[80:83], v[164:167], v[212:215], v[80:83]
	v_mfma_f32_16x16x32_bf16 v[76:79], v[156:159], v[248:251], v[76:79]
	v_mfma_f32_16x16x32_bf16 v[72:75], v[164:167], v[248:251], v[72:75]
	s_barrier
	s_setprio 0
	s_add_i32 s66, s67, s38
	v_lshl_add_u64 v[194:195], s[12:13], 0, v[172:173]
	s_mov_b32 m0, s66
	ds_read_b128 v[168:171], v242 offset:16384
	ds_read_b128 v[186:189], v242 offset:17408
	ds_read_b128 v[190:193], v242 offset:18432
	ds_read_b128 v[204:207], v242 offset:19456
	ds_read_b128 v[208:211], v242 offset:20480
	ds_read_b128 v[212:215], v242 offset:21504
	ds_read_b128 v[244:247], v242 offset:22528
	ds_read_b128 v[248:251], v242 offset:23552
	global_load_lds_dwordx4 v[194:195], off
	s_add_i32 m0, s66, 0x2000
	s_add_u32 s66, s12, 0x80000
	v_lshl_add_u64 v[196:197], s[12:13], 0, v[176:177]
	s_addc_u32 s67, s13, 0
	s_add_i32 s43, s43, s38
	global_load_lds_dwordx4 v[196:197], off
	v_lshl_add_u64 v[198:199], s[66:67], 0, v[172:173]
	s_mov_b32 m0, s43
	v_lshl_add_u64 v[200:201], s[16:17], 0, v[174:175]
	global_load_lds_dwordx4 v[198:199], off
	v_lshl_add_u64 v[198:199], s[66:67], 0, v[176:177]
	s_add_i32 m0, s43, 0x2000
	s_nop 0
	global_load_lds_dwordx4 v[198:199], off
	v_lshl_add_u64 v[198:199], s[16:17], 0, v[0:1]
	s_mov_b32 m0, s39
	s_nop 0
	global_load_lds_dwordx4 v[198:199], off
	s_mov_b32 m0, s46
	s_nop 0
	global_load_lds_dwordx4 v[200:201], off
	s_waitcnt vmcnt(8)
	s_waitcnt lgkmcnt(0)
	s_setprio 1
	s_barrier
	v_mfma_f32_16x16x32_bf16 v[68:71], v[136:139], v[168:171], v[68:71]
	v_mfma_f32_16x16x32_bf16 v[64:67], v[144:147], v[168:171], v[64:67]
	v_mfma_f32_16x16x32_bf16 v[60:63], v[136:139], v[190:193], v[60:63]
	v_mfma_f32_16x16x32_bf16 v[56:59], v[144:147], v[190:193], v[56:59]
	v_mfma_f32_16x16x32_bf16 v[52:55], v[136:139], v[208:211], v[52:55]
	v_mfma_f32_16x16x32_bf16 v[48:51], v[144:147], v[208:211], v[48:51]
	v_mfma_f32_16x16x32_bf16 v[44:47], v[136:139], v[244:247], v[44:47]
	v_mfma_f32_16x16x32_bf16 v[40:43], v[144:147], v[244:247], v[40:43]
	v_mfma_f32_16x16x32_bf16 v[68:71], v[140:143], v[186:189], v[68:71]
	v_mfma_f32_16x16x32_bf16 v[64:67], v[148:151], v[186:189], v[64:67]
	v_mfma_f32_16x16x32_bf16 v[60:63], v[140:143], v[204:207], v[60:63]
	v_mfma_f32_16x16x32_bf16 v[56:59], v[148:151], v[204:207], v[56:59]
	v_mfma_f32_16x16x32_bf16 v[52:55], v[140:143], v[212:215], v[52:55]
	v_mfma_f32_16x16x32_bf16 v[48:51], v[148:151], v[212:215], v[48:51]
	v_mfma_f32_16x16x32_bf16 v[44:47], v[140:143], v[248:251], v[44:47]
	v_mfma_f32_16x16x32_bf16 v[40:43], v[148:151], v[248:251], v[40:43]
	s_setprio 0
	s_setprio 1
	v_mfma_f32_16x16x32_bf16 v[36:39], v[152:155], v[168:171], v[36:39]
	v_mfma_f32_16x16x32_bf16 v[32:35], v[160:163], v[168:171], v[32:35]
	v_mfma_f32_16x16x32_bf16 v[28:31], v[152:155], v[190:193], v[28:31]
	v_mfma_f32_16x16x32_bf16 v[24:27], v[160:163], v[190:193], v[24:27]
	v_mfma_f32_16x16x32_bf16 v[20:23], v[152:155], v[208:211], v[20:23]
	v_mfma_f32_16x16x32_bf16 v[16:19], v[160:163], v[208:211], v[16:19]
	v_mfma_f32_16x16x32_bf16 v[12:15], v[152:155], v[244:247], v[12:15]
	v_mfma_f32_16x16x32_bf16 v[4:7], v[160:163], v[244:247], v[4:7]
	v_mfma_f32_16x16x32_bf16 v[36:39], v[156:159], v[186:189], v[36:39]
	v_mfma_f32_16x16x32_bf16 v[32:35], v[164:167], v[186:189], v[32:35]
	v_mfma_f32_16x16x32_bf16 v[28:31], v[156:159], v[204:207], v[28:31]
	v_mfma_f32_16x16x32_bf16 v[24:27], v[164:167], v[204:207], v[24:27]
	v_mfma_f32_16x16x32_bf16 v[20:23], v[156:159], v[212:215], v[20:23]
	v_mfma_f32_16x16x32_bf16 v[16:19], v[164:167], v[212:215], v[16:19]
	v_mfma_f32_16x16x32_bf16 v[12:15], v[156:159], v[248:251], v[12:15]
	v_mfma_f32_16x16x32_bf16 v[4:7], v[164:167], v[248:251], v[4:7]
	s_barrier
	s_setprio 0
	s_add_i32 s43, 0, 0x18000
	s_add_i32 s66, 0, 0x1c000
	v_add_u32_e32 v148, s43, v229
	v_add_u32_e32 v164, s66, v229
	ds_read_b128 v[136:139], v148
	ds_read_b128 v[140:143], v148 offset:1024
	ds_read_b128 v[144:147], v148 offset:2048
	ds_read_b128 v[148:151], v148 offset:3072
	ds_read_b128 v[152:155], v164
	ds_read_b128 v[156:159], v164 offset:1024
	ds_read_b128 v[160:163], v164 offset:2048
	ds_read_b128 v[164:167], v164 offset:3072
	s_add_u32 s16, s16, 0x80000
	s_addc_u32 s17, s17, 0
	s_mov_b32 m0, s47
	v_lshl_add_u64 v[202:203], s[16:17], 0, v[0:1]
	ds_read_b128 v[168:171], v242 offset:32768
	ds_read_b128 v[186:189], v242 offset:33792
	ds_read_b128 v[190:193], v242 offset:34816
	ds_read_b128 v[204:207], v242 offset:35840
	ds_read_b128 v[208:211], v242 offset:36864
	ds_read_b128 v[212:215], v242 offset:37888
	ds_read_b128 v[244:247], v242 offset:38912
	ds_read_b128 v[248:251], v242 offset:39936
	global_load_lds_dwordx4 v[202:203], off
	v_lshl_add_u64 v[202:203], s[16:17], 0, v[174:175]
	s_mov_b32 m0, s51
	s_nop 0
	global_load_lds_dwordx4 v[202:203], off
	s_waitcnt vmcnt(8)
	s_waitcnt lgkmcnt(0)
	s_setprio 1
	s_barrier
	v_mfma_f32_16x16x32_bf16 v[8:11], v[136:139], v[168:171], v[8:11]
	v_mfma_f32_16x16x32_bf16 v[128:131], v[144:147], v[168:171], v[128:131]
	v_mfma_f32_16x16x32_bf16 v[124:127], v[136:139], v[190:193], v[124:127]
	v_mfma_f32_16x16x32_bf16 v[120:123], v[144:147], v[190:193], v[120:123]
	v_mfma_f32_16x16x32_bf16 v[116:119], v[136:139], v[208:211], v[116:119]
	v_mfma_f32_16x16x32_bf16 v[112:115], v[144:147], v[208:211], v[112:115]
	v_mfma_f32_16x16x32_bf16 v[108:111], v[136:139], v[244:247], v[108:111]
	v_mfma_f32_16x16x32_bf16 v[104:107], v[144:147], v[244:247], v[104:107]
	v_mfma_f32_16x16x32_bf16 v[8:11], v[140:143], v[186:189], v[8:11]
	v_mfma_f32_16x16x32_bf16 v[128:131], v[148:151], v[186:189], v[128:131]
	v_mfma_f32_16x16x32_bf16 v[124:127], v[140:143], v[204:207], v[124:127]
	v_mfma_f32_16x16x32_bf16 v[120:123], v[148:151], v[204:207], v[120:123]
	v_mfma_f32_16x16x32_bf16 v[116:119], v[140:143], v[212:215], v[116:119]
	v_mfma_f32_16x16x32_bf16 v[112:115], v[148:151], v[212:215], v[112:115]
	v_mfma_f32_16x16x32_bf16 v[108:111], v[140:143], v[248:251], v[108:111]
	v_mfma_f32_16x16x32_bf16 v[104:107], v[148:151], v[248:251], v[104:107]
	s_setprio 0
	s_setprio 1
	v_mfma_f32_16x16x32_bf16 v[100:103], v[152:155], v[168:171], v[100:103]
	v_mfma_f32_16x16x32_bf16 v[96:99], v[160:163], v[168:171], v[96:99]
	v_mfma_f32_16x16x32_bf16 v[92:95], v[152:155], v[190:193], v[92:95]
	v_mfma_f32_16x16x32_bf16 v[88:91], v[160:163], v[190:193], v[88:91]
	v_mfma_f32_16x16x32_bf16 v[84:87], v[152:155], v[208:211], v[84:87]
	v_mfma_f32_16x16x32_bf16 v[80:83], v[160:163], v[208:211], v[80:83]
	v_mfma_f32_16x16x32_bf16 v[76:79], v[152:155], v[244:247], v[76:79]
	v_mfma_f32_16x16x32_bf16 v[72:75], v[160:163], v[244:247], v[72:75]
	v_mfma_f32_16x16x32_bf16 v[100:103], v[156:159], v[186:189], v[100:103]
	v_mfma_f32_16x16x32_bf16 v[96:99], v[164:167], v[186:189], v[96:99]
	v_mfma_f32_16x16x32_bf16 v[92:95], v[156:159], v[204:207], v[92:95]
	v_mfma_f32_16x16x32_bf16 v[88:91], v[164:167], v[204:207], v[88:91]
	v_mfma_f32_16x16x32_bf16 v[84:87], v[156:159], v[212:215], v[84:87]
	v_mfma_f32_16x16x32_bf16 v[80:83], v[164:167], v[212:215], v[80:83]
	v_mfma_f32_16x16x32_bf16 v[76:79], v[156:159], v[248:251], v[76:79]
	v_mfma_f32_16x16x32_bf16 v[72:75], v[164:167], v[248:251], v[72:75]
	s_barrier
	s_setprio 0
	s_add_i32 s16, s43, s38
	v_lshl_add_u64 v[194:195], v[194:195], 0, s[70:71]
	s_mov_b32 m0, s16
	ds_read_b128 v[168:171], v242 offset:49152
	ds_read_b128 v[186:189], v242 offset:50176
	ds_read_b128 v[190:193], v242 offset:51200
	ds_read_b128 v[204:207], v242 offset:52224
	ds_read_b128 v[208:211], v242 offset:53248
	ds_read_b128 v[212:215], v242 offset:54272
	ds_read_b128 v[244:247], v242 offset:55296
	ds_read_b128 v[248:251], v242 offset:56320
	global_load_lds_dwordx4 v[194:195], off
	s_add_i32 m0, s16, 0x2000
	s_add_u32 s12, s12, 0x80080
	v_lshl_add_u64 v[194:195], v[196:197], 0, s[70:71]
	s_addc_u32 s13, s13, 0
	s_add_i32 s16, s66, s38
	global_load_lds_dwordx4 v[194:195], off
	v_lshl_add_u64 v[194:195], s[12:13], 0, v[172:173]
	s_mov_b32 m0, s16
	s_nop 0
	global_load_lds_dwordx4 v[194:195], off
	v_lshl_add_u64 v[194:195], s[12:13], 0, v[176:177]
	s_add_i32 m0, s16, 0x2000
	s_nop 0
	global_load_lds_dwordx4 v[194:195], off
	v_lshl_add_u64 v[194:195], v[198:199], 0, s[70:71]
	s_mov_b32 m0, s52
	s_nop 0
	global_load_lds_dwordx4 v[194:195], off
	v_lshl_add_u64 v[194:195], v[200:201], 0, s[70:71]
	s_mov_b32 m0, s54
	s_nop 0
	global_load_lds_dwordx4 v[194:195], off
	s_waitcnt vmcnt(8)
	s_waitcnt lgkmcnt(0)
	s_setprio 1
	s_barrier
	v_mfma_f32_16x16x32_bf16 v[68:71], v[136:139], v[168:171], v[68:71]
	v_mfma_f32_16x16x32_bf16 v[64:67], v[144:147], v[168:171], v[64:67]
	v_mfma_f32_16x16x32_bf16 v[60:63], v[136:139], v[190:193], v[60:63]
	v_mfma_f32_16x16x32_bf16 v[56:59], v[144:147], v[190:193], v[56:59]
	v_mfma_f32_16x16x32_bf16 v[52:55], v[136:139], v[208:211], v[52:55]
	v_mfma_f32_16x16x32_bf16 v[48:51], v[144:147], v[208:211], v[48:51]
	v_mfma_f32_16x16x32_bf16 v[44:47], v[136:139], v[244:247], v[44:47]
	v_mfma_f32_16x16x32_bf16 v[40:43], v[144:147], v[244:247], v[40:43]
	v_mfma_f32_16x16x32_bf16 v[68:71], v[140:143], v[186:189], v[68:71]
	v_mfma_f32_16x16x32_bf16 v[64:67], v[148:151], v[186:189], v[64:67]
	v_mfma_f32_16x16x32_bf16 v[60:63], v[140:143], v[204:207], v[60:63]
	v_mfma_f32_16x16x32_bf16 v[56:59], v[148:151], v[204:207], v[56:59]
	v_mfma_f32_16x16x32_bf16 v[52:55], v[140:143], v[212:215], v[52:55]
	v_mfma_f32_16x16x32_bf16 v[48:51], v[148:151], v[212:215], v[48:51]
	v_mfma_f32_16x16x32_bf16 v[44:47], v[140:143], v[248:251], v[44:47]
	v_mfma_f32_16x16x32_bf16 v[40:43], v[148:151], v[248:251], v[40:43]
	s_setprio 0
	s_setprio 1
	v_mfma_f32_16x16x32_bf16 v[36:39], v[152:155], v[168:171], v[36:39]
	v_mfma_f32_16x16x32_bf16 v[32:35], v[160:163], v[168:171], v[32:35]
	v_mfma_f32_16x16x32_bf16 v[28:31], v[152:155], v[190:193], v[28:31]
	v_mfma_f32_16x16x32_bf16 v[24:27], v[160:163], v[190:193], v[24:27]
	v_mfma_f32_16x16x32_bf16 v[20:23], v[152:155], v[208:211], v[20:23]
	v_mfma_f32_16x16x32_bf16 v[16:19], v[160:163], v[208:211], v[16:19]
	v_mfma_f32_16x16x32_bf16 v[12:15], v[152:155], v[244:247], v[12:15]
	v_mfma_f32_16x16x32_bf16 v[4:7], v[160:163], v[244:247], v[4:7]
	v_mfma_f32_16x16x32_bf16 v[36:39], v[156:159], v[186:189], v[36:39]
	v_mfma_f32_16x16x32_bf16 v[32:35], v[164:167], v[186:189], v[32:35]
	v_mfma_f32_16x16x32_bf16 v[28:31], v[156:159], v[204:207], v[28:31]
	v_mfma_f32_16x16x32_bf16 v[24:27], v[164:167], v[204:207], v[24:27]
	v_mfma_f32_16x16x32_bf16 v[20:23], v[156:159], v[212:215], v[20:23]
	v_mfma_f32_16x16x32_bf16 v[16:19], v[164:167], v[212:215], v[16:19]
	v_mfma_f32_16x16x32_bf16 v[12:15], v[156:159], v[248:251], v[12:15]
	v_mfma_f32_16x16x32_bf16 v[4:7], v[164:167], v[248:251], v[4:7]
	s_barrier
	s_setprio 0
	s_add_i32 s42, s42, 2
	s_add_u32 s8, s8, 0x100
	s_addc_u32 s9, s9, 0
	s_cmp_gt_u32 s42, 29
	s_cbranch_scc0 .LBB0_319
	s_and_b64 vcc, exec, s[22:23]
	s_cbranch_vccz .LBB0_322
	s_barrier

.LBB0_803:
	s_add_u32 s12, s28, s8
	s_addc_u32 s13, s29, s9
	s_add_u32 s12, s12, 0x100
	s_addc_u32 s13, s13, 0
	s_add_u32 s81, s84, s8
	s_addc_u32 s83, s85, s9
	s_add_i32 s95, 0, 0x10000
	s_cmpk_eq_i32 s8, 0xf00
	s_cselect_b32 s37, s27, s13
	s_cselect_b32 s36, s42, s12
	s_cselect_b32 s13, s25, s83
	s_cselect_b32 s12, s43, s81
	s_add_i32 s81, 0, 0x14000
	v_add_u32_e32 v148, s95, v207
	v_add_u32_e32 v176, s81, v207
	ds_read_b128 v[136:139], v148
	ds_read_b128 v[140:143], v148 offset:1024
	ds_read_b128 v[144:147], v148 offset:2048
	ds_read_b128 v[148:151], v148 offset:3072
	ds_read_b128 v[152:155], v176
	ds_read_b128 v[156:159], v176 offset:1024
	ds_read_b128 v[160:163], v176 offset:2048
	s_waitcnt lgkmcnt(0)
	ds_read_b128 v[176:179], v176 offset:3072
	v_lshl_add_u64 v[196:197], v[132:133], 0, s[8:9]
	s_add_i32 m0, s75, 0xc000
	ds_read_b128 v[180:183], v209
	ds_read_b128 v[184:187], v209 offset:1024
	ds_read_b128 v[188:191], v209 offset:2048
	ds_read_b128 v[192:195], v209 offset:3072
	ds_read_b128 v[212:215], v209 offset:4096
	ds_read_b128 v[226:229], v209 offset:5120
	ds_read_b128 v[230:233], v209 offset:6144
	ds_read_b128 v[234:237], v209 offset:7168
	global_load_lds_dwordx4 v[196:197], off
	v_lshl_add_u64 v[196:197], v[134:135], 0, s[8:9]
	s_add_i32 m0, s75, 0xe000
	s_nop 0
	global_load_lds_dwordx4 v[196:197], off
	s_waitcnt vmcnt(8)
	s_waitcnt lgkmcnt(0)
	s_setprio 1
	s_barrier
	v_mfma_f32_16x16x32_bf16 v[8:11], v[136:139], v[180:183], v[8:11]
	v_mfma_f32_16x16x32_bf16 v[128:131], v[144:147], v[180:183], v[128:131]
	v_mfma_f32_16x16x32_bf16 v[124:127], v[136:139], v[188:191], v[124:127]
	v_mfma_f32_16x16x32_bf16 v[120:123], v[144:147], v[188:191], v[120:123]
	v_mfma_f32_16x16x32_bf16 v[116:119], v[136:139], v[212:215], v[116:119]
	v_mfma_f32_16x16x32_bf16 v[112:115], v[144:147], v[212:215], v[112:115]
	v_mfma_f32_16x16x32_bf16 v[108:111], v[136:139], v[230:233], v[108:111]
	v_mfma_f32_16x16x32_bf16 v[104:107], v[144:147], v[230:233], v[104:107]
	v_mfma_f32_16x16x32_bf16 v[8:11], v[140:143], v[184:187], v[8:11]
	v_mfma_f32_16x16x32_bf16 v[128:131], v[148:151], v[184:187], v[128:131]
	v_mfma_f32_16x16x32_bf16 v[124:127], v[140:143], v[192:195], v[124:127]
	v_mfma_f32_16x16x32_bf16 v[120:123], v[148:151], v[192:195], v[120:123]
	v_mfma_f32_16x16x32_bf16 v[116:119], v[140:143], v[226:229], v[116:119]
	v_mfma_f32_16x16x32_bf16 v[112:115], v[148:151], v[226:229], v[112:115]
	v_mfma_f32_16x16x32_bf16 v[108:111], v[140:143], v[234:237], v[108:111]
	v_mfma_f32_16x16x32_bf16 v[104:107], v[148:151], v[234:237], v[104:107]
	s_setprio 0
	s_setprio 1
	v_mfma_f32_16x16x32_bf16 v[100:103], v[152:155], v[180:183], v[100:103]
	v_mfma_f32_16x16x32_bf16 v[96:99], v[160:163], v[180:183], v[96:99]
	v_mfma_f32_16x16x32_bf16 v[92:95], v[152:155], v[188:191], v[92:95]
	v_mfma_f32_16x16x32_bf16 v[88:91], v[160:163], v[188:191], v[88:91]
	v_mfma_f32_16x16x32_bf16 v[84:87], v[152:155], v[212:215], v[84:87]
	v_mfma_f32_16x16x32_bf16 v[80:83], v[160:163], v[212:215], v[80:83]
	v_mfma_f32_16x16x32_bf16 v[76:79], v[152:155], v[230:233], v[76:79]
	v_mfma_f32_16x16x32_bf16 v[72:75], v[160:163], v[230:233], v[72:75]
	v_mfma_f32_16x16x32_bf16 v[100:103], v[156:159], v[184:187], v[100:103]
	v_mfma_f32_16x16x32_bf16 v[96:99], v[176:179], v[184:187], v[96:99]
	v_mfma_f32_16x16x32_bf16 v[92:95], v[156:159], v[192:195], v[92:95]
	v_mfma_f32_16x16x32_bf16 v[88:91], v[176:179], v[192:195], v[88:91]
	v_mfma_f32_16x16x32_bf16 v[84:87], v[156:159], v[226:229], v[84:87]
	v_mfma_f32_16x16x32_bf16 v[80:83], v[176:179], v[226:229], v[80:83]
	v_mfma_f32_16x16x32_bf16 v[76:79], v[156:159], v[234:237], v[76:79]
	v_mfma_f32_16x16x32_bf16 v[72:75], v[176:179], v[234:237], v[72:75]
	s_barrier
	s_setprio 0
	s_add_i32 s83, s95, s74
	v_lshl_add_u64 v[196:197], s[12:13], 0, v[164:165]
	s_mov_b32 m0, s83
	ds_read_b128 v[180:183], v209 offset:16384
	ds_read_b128 v[184:187], v209 offset:17408
	ds_read_b128 v[188:191], v209 offset:18432
	ds_read_b128 v[192:195], v209 offset:19456
	ds_read_b128 v[212:215], v209 offset:20480
	ds_read_b128 v[226:229], v209 offset:21504
	ds_read_b128 v[230:233], v209 offset:22528
	ds_read_b128 v[234:237], v209 offset:23552
	global_load_lds_dwordx4 v[196:197], off
	s_add_i32 m0, s83, 0x2000
	s_add_u32 vcc_lo, s12, 0x80000
	v_lshl_add_u64 v[198:199], s[12:13], 0, v[168:169]
	s_addc_u32 vcc_hi, s13, 0
	s_add_i32 s81, s81, s74
	global_load_lds_dwordx4 v[198:199], off
	v_lshl_add_u64 v[200:201], vcc, 0, v[164:165]
	s_mov_b32 m0, s81
	v_lshl_add_u64 v[202:203], s[36:37], 0, v[166:167]
	global_load_lds_dwordx4 v[200:201], off
	v_lshl_add_u64 v[200:201], vcc, 0, v[168:169]
	s_add_i32 m0, s81, 0x2000
	s_nop 0
	global_load_lds_dwordx4 v[200:201], off
	v_lshl_add_u64 v[200:201], s[36:37], 0, v[0:1]
	s_mov_b32 m0, s75
	s_nop 0
	global_load_lds_dwordx4 v[200:201], off
	s_mov_b32 m0, s15
	s_nop 0
	global_load_lds_dwordx4 v[202:203], off
	s_waitcnt vmcnt(8)
	s_waitcnt lgkmcnt(0)
	s_setprio 1
	s_barrier
	v_mfma_f32_16x16x32_bf16 v[68:71], v[136:139], v[180:183], v[68:71]
	v_mfma_f32_16x16x32_bf16 v[64:67], v[144:147], v[180:183], v[64:67]
	v_mfma_f32_16x16x32_bf16 v[60:63], v[136:139], v[188:191], v[60:63]
	v_mfma_f32_16x16x32_bf16 v[56:59], v[144:147], v[188:191], v[56:59]
	v_mfma_f32_16x16x32_bf16 v[52:55], v[136:139], v[212:215], v[52:55]
	v_mfma_f32_16x16x32_bf16 v[48:51], v[144:147], v[212:215], v[48:51]
	v_mfma_f32_16x16x32_bf16 v[44:47], v[136:139], v[230:233], v[44:47]
	v_mfma_f32_16x16x32_bf16 v[40:43], v[144:147], v[230:233], v[40:43]
	v_mfma_f32_16x16x32_bf16 v[68:71], v[140:143], v[184:187], v[68:71]
	v_mfma_f32_16x16x32_bf16 v[64:67], v[148:151], v[184:187], v[64:67]
	v_mfma_f32_16x16x32_bf16 v[60:63], v[140:143], v[192:195], v[60:63]
	v_mfma_f32_16x16x32_bf16 v[56:59], v[148:151], v[192:195], v[56:59]
	v_mfma_f32_16x16x32_bf16 v[52:55], v[140:143], v[226:229], v[52:55]
	v_mfma_f32_16x16x32_bf16 v[48:51], v[148:151], v[226:229], v[48:51]
	v_mfma_f32_16x16x32_bf16 v[44:47], v[140:143], v[234:237], v[44:47]
	v_mfma_f32_16x16x32_bf16 v[40:43], v[148:151], v[234:237], v[40:43]
	s_setprio 0
	s_setprio 1
	v_mfma_f32_16x16x32_bf16 v[36:39], v[152:155], v[180:183], v[36:39]
	v_mfma_f32_16x16x32_bf16 v[32:35], v[160:163], v[180:183], v[32:35]
	v_mfma_f32_16x16x32_bf16 v[28:31], v[152:155], v[188:191], v[28:31]
	v_mfma_f32_16x16x32_bf16 v[24:27], v[160:163], v[188:191], v[24:27]
	v_mfma_f32_16x16x32_bf16 v[20:23], v[152:155], v[212:215], v[20:23]
	v_mfma_f32_16x16x32_bf16 v[16:19], v[160:163], v[212:215], v[16:19]
	v_mfma_f32_16x16x32_bf16 v[12:15], v[152:155], v[230:233], v[12:15]
	v_mfma_f32_16x16x32_bf16 v[4:7], v[160:163], v[230:233], v[4:7]
	v_mfma_f32_16x16x32_bf16 v[36:39], v[156:159], v[184:187], v[36:39]
	v_mfma_f32_16x16x32_bf16 v[32:35], v[176:179], v[184:187], v[32:35]
	v_mfma_f32_16x16x32_bf16 v[28:31], v[156:159], v[192:195], v[28:31]
	v_mfma_f32_16x16x32_bf16 v[24:27], v[176:179], v[192:195], v[24:27]
	v_mfma_f32_16x16x32_bf16 v[20:23], v[156:159], v[226:229], v[20:23]
	v_mfma_f32_16x16x32_bf16 v[16:19], v[176:179], v[226:229], v[16:19]
	v_mfma_f32_16x16x32_bf16 v[12:15], v[156:159], v[234:237], v[12:15]
	v_mfma_f32_16x16x32_bf16 v[4:7], v[176:179], v[234:237], v[4:7]
	s_barrier
	s_setprio 0
	s_add_i32 s81, 0, 0x18000
	s_add_i32 s83, 0, 0x1c000
	v_add_u32_e32 v148, s81, v207
	v_add_u32_e32 v176, s83, v207
	ds_read_b128 v[136:139], v148
	ds_read_b128 v[140:143], v148 offset:1024
	ds_read_b128 v[144:147], v148 offset:2048
	ds_read_b128 v[148:151], v148 offset:3072
	ds_read_b128 v[152:155], v176
	ds_read_b128 v[156:159], v176 offset:1024
	ds_read_b128 v[160:163], v176 offset:2048
	ds_read_b128 v[176:179], v176 offset:3072
	s_add_u32 s36, s36, 0x80000
	s_addc_u32 s37, s37, 0
	s_mov_b32 m0, s38
	v_lshl_add_u64 v[216:217], s[36:37], 0, v[0:1]
	ds_read_b128 v[180:183], v209 offset:32768
	ds_read_b128 v[184:187], v209 offset:33792
	ds_read_b128 v[188:191], v209 offset:34816
	ds_read_b128 v[192:195], v209 offset:35840
	ds_read_b128 v[212:215], v209 offset:36864
	ds_read_b128 v[226:229], v209 offset:37888
	ds_read_b128 v[230:233], v209 offset:38912
	ds_read_b128 v[234:237], v209 offset:39936
	global_load_lds_dwordx4 v[216:217], off
	v_lshl_add_u64 v[216:217], s[36:37], 0, v[166:167]
	s_mov_b32 m0, s39
	s_nop 0
	global_load_lds_dwordx4 v[216:217], off
	s_waitcnt vmcnt(8)
	s_waitcnt lgkmcnt(0)
	s_setprio 1
	s_barrier
	v_mfma_f32_16x16x32_bf16 v[8:11], v[136:139], v[180:183], v[8:11]
	v_mfma_f32_16x16x32_bf16 v[128:131], v[144:147], v[180:183], v[128:131]
	v_mfma_f32_16x16x32_bf16 v[124:127], v[136:139], v[188:191], v[124:127]
	v_mfma_f32_16x16x32_bf16 v[120:123], v[144:147], v[188:191], v[120:123]
	v_mfma_f32_16x16x32_bf16 v[116:119], v[136:139], v[212:215], v[116:119]
	v_mfma_f32_16x16x32_bf16 v[112:115], v[144:147], v[212:215], v[112:115]
	v_mfma_f32_16x16x32_bf16 v[108:111], v[136:139], v[230:233], v[108:111]
	v_mfma_f32_16x16x32_bf16 v[104:107], v[144:147], v[230:233], v[104:107]
	v_mfma_f32_16x16x32_bf16 v[8:11], v[140:143], v[184:187], v[8:11]
	v_mfma_f32_16x16x32_bf16 v[128:131], v[148:151], v[184:187], v[128:131]
	v_mfma_f32_16x16x32_bf16 v[124:127], v[140:143], v[192:195], v[124:127]
	v_mfma_f32_16x16x32_bf16 v[120:123], v[148:151], v[192:195], v[120:123]
	v_mfma_f32_16x16x32_bf16 v[116:119], v[140:143], v[226:229], v[116:119]
	v_mfma_f32_16x16x32_bf16 v[112:115], v[148:151], v[226:229], v[112:115]
	v_mfma_f32_16x16x32_bf16 v[108:111], v[140:143], v[234:237], v[108:111]
	v_mfma_f32_16x16x32_bf16 v[104:107], v[148:151], v[234:237], v[104:107]
	s_setprio 0
	s_setprio 1
	v_mfma_f32_16x16x32_bf16 v[100:103], v[152:155], v[180:183], v[100:103]
	v_mfma_f32_16x16x32_bf16 v[96:99], v[160:163], v[180:183], v[96:99]
	v_mfma_f32_16x16x32_bf16 v[92:95], v[152:155], v[188:191], v[92:95]
	v_mfma_f32_16x16x32_bf16 v[88:91], v[160:163], v[188:191], v[88:91]
	v_mfma_f32_16x16x32_bf16 v[84:87], v[152:155], v[212:215], v[84:87]
	v_mfma_f32_16x16x32_bf16 v[80:83], v[160:163], v[212:215], v[80:83]
	v_mfma_f32_16x16x32_bf16 v[76:79], v[152:155], v[230:233], v[76:79]
	v_mfma_f32_16x16x32_bf16 v[72:75], v[160:163], v[230:233], v[72:75]
	v_mfma_f32_16x16x32_bf16 v[100:103], v[156:159], v[184:187], v[100:103]
	v_mfma_f32_16x16x32_bf16 v[96:99], v[176:179], v[184:187], v[96:99]
	v_mfma_f32_16x16x32_bf16 v[92:95], v[156:159], v[192:195], v[92:95]
	v_mfma_f32_16x16x32_bf16 v[88:91], v[176:179], v[192:195], v[88:91]
	v_mfma_f32_16x16x32_bf16 v[84:87], v[156:159], v[226:229], v[84:87]
	v_mfma_f32_16x16x32_bf16 v[80:83], v[176:179], v[226:229], v[80:83]
	v_mfma_f32_16x16x32_bf16 v[76:79], v[156:159], v[234:237], v[76:79]
	v_mfma_f32_16x16x32_bf16 v[72:75], v[176:179], v[234:237], v[72:75]
	s_barrier
	s_setprio 0
	s_add_i32 s36, s81, s74
	v_lshl_add_u64 v[196:197], v[196:197], 0, s[70:71]
	s_mov_b32 m0, s36
	ds_read_b128 v[180:183], v209 offset:49152
	ds_read_b128 v[184:187], v209 offset:50176
	ds_read_b128 v[188:191], v209 offset:51200
	ds_read_b128 v[192:195], v209 offset:52224
	ds_read_b128 v[212:215], v209 offset:53248
	ds_read_b128 v[226:229], v209 offset:54272
	ds_read_b128 v[230:233], v209 offset:55296
	ds_read_b128 v[234:237], v209 offset:56320
	global_load_lds_dwordx4 v[196:197], off
	s_add_i32 m0, s36, 0x2000
	s_add_u32 s12, s12, 0x80080
	v_lshl_add_u64 v[196:197], v[198:199], 0, s[70:71]
	s_addc_u32 s13, s13, 0
	s_add_i32 s36, s83, s74
	global_load_lds_dwordx4 v[196:197], off
	v_lshl_add_u64 v[196:197], s[12:13], 0, v[164:165]
	s_mov_b32 m0, s36
	s_nop 0
	global_load_lds_dwordx4 v[196:197], off
	v_lshl_add_u64 v[196:197], s[12:13], 0, v[168:169]
	s_add_i32 m0, s36, 0x2000
	s_nop 0
	global_load_lds_dwordx4 v[196:197], off
	v_lshl_add_u64 v[196:197], v[200:201], 0, s[70:71]
	s_mov_b32 m0, s51
	s_nop 0
	global_load_lds_dwordx4 v[196:197], off
	v_lshl_add_u64 v[196:197], v[202:203], 0, s[70:71]
	s_mov_b32 m0, s92
	s_nop 0
	global_load_lds_dwordx4 v[196:197], off
	s_waitcnt vmcnt(8)
	s_waitcnt lgkmcnt(0)
	s_setprio 1
	s_barrier
	v_mfma_f32_16x16x32_bf16 v[68:71], v[136:139], v[180:183], v[68:71]
	v_mfma_f32_16x16x32_bf16 v[64:67], v[144:147], v[180:183], v[64:67]
	v_mfma_f32_16x16x32_bf16 v[60:63], v[136:139], v[188:191], v[60:63]
	v_mfma_f32_16x16x32_bf16 v[56:59], v[144:147], v[188:191], v[56:59]
	v_mfma_f32_16x16x32_bf16 v[52:55], v[136:139], v[212:215], v[52:55]
	v_mfma_f32_16x16x32_bf16 v[48:51], v[144:147], v[212:215], v[48:51]
	v_mfma_f32_16x16x32_bf16 v[44:47], v[136:139], v[230:233], v[44:47]
	v_mfma_f32_16x16x32_bf16 v[40:43], v[144:147], v[230:233], v[40:43]
	v_mfma_f32_16x16x32_bf16 v[68:71], v[140:143], v[184:187], v[68:71]
	v_mfma_f32_16x16x32_bf16 v[64:67], v[148:151], v[184:187], v[64:67]
	v_mfma_f32_16x16x32_bf16 v[60:63], v[140:143], v[192:195], v[60:63]
	v_mfma_f32_16x16x32_bf16 v[56:59], v[148:151], v[192:195], v[56:59]
	v_mfma_f32_16x16x32_bf16 v[52:55], v[140:143], v[226:229], v[52:55]
	v_mfma_f32_16x16x32_bf16 v[48:51], v[148:151], v[226:229], v[48:51]
	v_mfma_f32_16x16x32_bf16 v[44:47], v[140:143], v[234:237], v[44:47]
	v_mfma_f32_16x16x32_bf16 v[40:43], v[148:151], v[234:237], v[40:43]
	s_setprio 0
	s_setprio 1
	v_mfma_f32_16x16x32_bf16 v[36:39], v[152:155], v[180:183], v[36:39]
	v_mfma_f32_16x16x32_bf16 v[32:35], v[160:163], v[180:183], v[32:35]
	v_mfma_f32_16x16x32_bf16 v[28:31], v[152:155], v[188:191], v[28:31]
	v_mfma_f32_16x16x32_bf16 v[24:27], v[160:163], v[188:191], v[24:27]
	v_mfma_f32_16x16x32_bf16 v[20:23], v[152:155], v[212:215], v[20:23]
	v_mfma_f32_16x16x32_bf16 v[16:19], v[160:163], v[212:215], v[16:19]
	v_mfma_f32_16x16x32_bf16 v[12:15], v[152:155], v[230:233], v[12:15]
	v_mfma_f32_16x16x32_bf16 v[4:7], v[160:163], v[230:233], v[4:7]
	v_mfma_f32_16x16x32_bf16 v[36:39], v[156:159], v[184:187], v[36:39]
	v_mfma_f32_16x16x32_bf16 v[32:35], v[176:179], v[184:187], v[32:35]
	v_mfma_f32_16x16x32_bf16 v[28:31], v[156:159], v[192:195], v[28:31]
	v_mfma_f32_16x16x32_bf16 v[24:27], v[176:179], v[192:195], v[24:27]
	v_mfma_f32_16x16x32_bf16 v[20:23], v[156:159], v[226:229], v[20:23]
	v_mfma_f32_16x16x32_bf16 v[16:19], v[176:179], v[226:229], v[16:19]
	v_mfma_f32_16x16x32_bf16 v[12:15], v[156:159], v[234:237], v[12:15]
	v_mfma_f32_16x16x32_bf16 v[4:7], v[176:179], v[234:237], v[4:7]
	s_barrier
	s_setprio 0
	s_add_i32 s52, s52, 2
	s_add_u32 s8, s8, 0x100
	s_addc_u32 s9, s9, 0
	s_cmp_gt_u32 s52, 29
	s_cbranch_scc0 .LBB0_803
	s_and_b64 vcc, exec, s[22:23]
	s_cbranch_vccz .LBB0_806
	s_barrier

.LBB0_975:
	s_add_u32 s34, s30, 0xfff80080
	s_addc_u32 s35, s31, -1
	s_add_i32 s81, 0, 0x10000
	s_cmp_eq_u32 s75, 28
	s_cselect_b32 s37, s25, s35
	s_cselect_b32 s36, s66, s34
	s_cselect_b32 s35, s23, s74
	s_cselect_b32 s34, s67, s69
	s_add_i32 s83, 0, 0x14000
	v_add_u32_e32 v144, s81, v182
	v_add_u32_e32 v170, s83, v182
	ds_read_b128 v[132:135], v144
	ds_read_b128 v[136:139], v144 offset:1024
	ds_read_b128 v[140:143], v144 offset:2048
	ds_read_b128 v[144:147], v144 offset:3072
	ds_read_b128 v[148:151], v170
	ds_read_b128 v[152:155], v170 offset:1024
	ds_read_b128 v[156:159], v170 offset:2048
	ds_read_b128 v[170:173], v170 offset:3072
	v_lshl_add_u64 v[212:213], s[30:31], 0, v[166:167]
	s_add_i32 m0, s15, 0xc000
	ds_read_b128 v[174:177], v186
	ds_read_b128 v[178:181], v186 offset:1024
	ds_read_b128 v[188:191], v186 offset:2048
	ds_read_b128 v[192:195], v186 offset:3072
	ds_read_b128 v[196:199], v186 offset:4096
	ds_read_b128 v[200:203], v186 offset:5120
	ds_read_b128 v[204:207], v186 offset:6144
	ds_read_b128 v[208:211], v186 offset:7168
	global_load_lds_dwordx4 v[212:213], off
	v_lshl_add_u64 v[212:213], s[30:31], 0, v[168:169]
	s_add_i32 m0, s15, 0xe000
	s_nop 0
	global_load_lds_dwordx4 v[212:213], off
	s_waitcnt vmcnt(8)
	s_waitcnt lgkmcnt(0)
	s_setprio 1
	s_barrier
	v_mfma_f32_16x16x32_bf16 v[128:131], v[132:135], v[174:177], v[128:131]
	v_mfma_f32_16x16x32_bf16 v[124:127], v[140:143], v[174:177], v[124:127]
	v_mfma_f32_16x16x32_bf16 v[112:115], v[132:135], v[188:191], v[112:115]
	v_mfma_f32_16x16x32_bf16 v[108:111], v[140:143], v[188:191], v[108:111]
	v_mfma_f32_16x16x32_bf16 v[96:99], v[132:135], v[196:199], v[96:99]
	v_mfma_f32_16x16x32_bf16 v[92:95], v[140:143], v[196:199], v[92:95]
	v_mfma_f32_16x16x32_bf16 v[80:83], v[132:135], v[204:207], v[80:83]
	v_mfma_f32_16x16x32_bf16 v[76:79], v[140:143], v[204:207], v[76:79]
	v_mfma_f32_16x16x32_bf16 v[128:131], v[136:139], v[178:181], v[128:131]
	v_mfma_f32_16x16x32_bf16 v[124:127], v[144:147], v[178:181], v[124:127]
	v_mfma_f32_16x16x32_bf16 v[112:115], v[136:139], v[192:195], v[112:115]
	v_mfma_f32_16x16x32_bf16 v[108:111], v[144:147], v[192:195], v[108:111]
	v_mfma_f32_16x16x32_bf16 v[96:99], v[136:139], v[200:203], v[96:99]
	v_mfma_f32_16x16x32_bf16 v[92:95], v[144:147], v[200:203], v[92:95]
	v_mfma_f32_16x16x32_bf16 v[80:83], v[136:139], v[208:211], v[80:83]
	v_mfma_f32_16x16x32_bf16 v[76:79], v[144:147], v[208:211], v[76:79]
	s_setprio 0
	s_setprio 1
	v_mfma_f32_16x16x32_bf16 v[120:123], v[148:151], v[174:177], v[120:123]
	v_mfma_f32_16x16x32_bf16 v[116:119], v[156:159], v[174:177], v[116:119]
	v_mfma_f32_16x16x32_bf16 v[104:107], v[148:151], v[188:191], v[104:107]
	v_mfma_f32_16x16x32_bf16 v[100:103], v[156:159], v[188:191], v[100:103]
	v_mfma_f32_16x16x32_bf16 v[88:91], v[148:151], v[196:199], v[88:91]
	v_mfma_f32_16x16x32_bf16 v[84:87], v[156:159], v[196:199], v[84:87]
	v_mfma_f32_16x16x32_bf16 v[72:75], v[148:151], v[204:207], v[72:75]
	v_mfma_f32_16x16x32_bf16 v[68:71], v[156:159], v[204:207], v[68:71]
	v_mfma_f32_16x16x32_bf16 v[120:123], v[152:155], v[178:181], v[120:123]
	v_mfma_f32_16x16x32_bf16 v[116:119], v[170:173], v[178:181], v[116:119]
	v_mfma_f32_16x16x32_bf16 v[104:107], v[152:155], v[192:195], v[104:107]
	v_mfma_f32_16x16x32_bf16 v[100:103], v[170:173], v[192:195], v[100:103]
	v_mfma_f32_16x16x32_bf16 v[88:91], v[152:155], v[200:203], v[88:91]
	v_mfma_f32_16x16x32_bf16 v[84:87], v[170:173], v[200:203], v[84:87]
	v_mfma_f32_16x16x32_bf16 v[72:75], v[152:155], v[208:211], v[72:75]
	v_mfma_f32_16x16x32_bf16 v[68:71], v[170:173], v[208:211], v[68:71]
	s_barrier
	s_setprio 0
	s_add_i32 s81, s81, s0
	v_lshl_add_u64 v[212:213], s[34:35], 0, v[162:163]
	s_mov_b32 m0, s81
	ds_read_b128 v[174:177], v186 offset:16384
	ds_read_b128 v[178:181], v186 offset:17408
	ds_read_b128 v[188:191], v186 offset:18432
	ds_read_b128 v[192:195], v186 offset:19456
	ds_read_b128 v[196:199], v186 offset:20480
	ds_read_b128 v[200:203], v186 offset:21504
	ds_read_b128 v[204:207], v186 offset:22528
	ds_read_b128 v[208:211], v186 offset:23552
	global_load_lds_dwordx4 v[212:213], off
	s_add_i32 m0, s81, 0x2000
	s_add_u32 s84, s34, 0x80000
	v_lshl_add_u64 v[214:215], s[34:35], 0, v[0:1]
	s_addc_u32 s85, s35, 0
	s_add_i32 s81, s83, s0
	global_load_lds_dwordx4 v[214:215], off
	v_lshl_add_u64 v[216:217], s[84:85], 0, v[162:163]
	s_mov_b32 m0, s81
	v_lshl_add_u64 v[226:227], s[36:37], 0, v[160:161]
	global_load_lds_dwordx4 v[216:217], off
	v_lshl_add_u64 v[216:217], s[84:85], 0, v[0:1]
	s_add_i32 m0, s81, 0x2000
	s_nop 0
	global_load_lds_dwordx4 v[216:217], off
	v_lshl_add_u64 v[216:217], s[36:37], 0, v[164:165]
	s_mov_b32 m0, s15
	s_nop 0
	global_load_lds_dwordx4 v[216:217], off
	s_mov_b32 m0, s38
	s_nop 0
	global_load_lds_dwordx4 v[226:227], off
	s_waitcnt vmcnt(8)
	s_waitcnt lgkmcnt(0)
	s_setprio 1
	s_barrier
	v_mfma_f32_16x16x32_bf16 v[64:67], v[132:135], v[174:177], v[64:67]
	v_mfma_f32_16x16x32_bf16 v[60:63], v[140:143], v[174:177], v[60:63]
	v_mfma_f32_16x16x32_bf16 v[48:51], v[132:135], v[188:191], v[48:51]
	v_mfma_f32_16x16x32_bf16 v[44:47], v[140:143], v[188:191], v[44:47]
	v_mfma_f32_16x16x32_bf16 v[32:35], v[132:135], v[196:199], v[32:35]
	v_mfma_f32_16x16x32_bf16 v[28:31], v[140:143], v[196:199], v[28:31]
	v_mfma_f32_16x16x32_bf16 v[16:19], v[132:135], v[204:207], v[16:19]
	v_mfma_f32_16x16x32_bf16 v[12:15], v[140:143], v[204:207], v[12:15]
	v_mfma_f32_16x16x32_bf16 v[64:67], v[136:139], v[178:181], v[64:67]
	v_mfma_f32_16x16x32_bf16 v[60:63], v[144:147], v[178:181], v[60:63]
	v_mfma_f32_16x16x32_bf16 v[48:51], v[136:139], v[192:195], v[48:51]
	v_mfma_f32_16x16x32_bf16 v[44:47], v[144:147], v[192:195], v[44:47]
	v_mfma_f32_16x16x32_bf16 v[32:35], v[136:139], v[200:203], v[32:35]
	v_mfma_f32_16x16x32_bf16 v[28:31], v[144:147], v[200:203], v[28:31]
	v_mfma_f32_16x16x32_bf16 v[16:19], v[136:139], v[208:211], v[16:19]
	v_mfma_f32_16x16x32_bf16 v[12:15], v[144:147], v[208:211], v[12:15]
	s_setprio 0
	s_setprio 1
	v_mfma_f32_16x16x32_bf16 v[56:59], v[148:151], v[174:177], v[56:59]
	v_mfma_f32_16x16x32_bf16 v[52:55], v[156:159], v[174:177], v[52:55]
	v_mfma_f32_16x16x32_bf16 v[40:43], v[148:151], v[188:191], v[40:43]
	v_mfma_f32_16x16x32_bf16 v[36:39], v[156:159], v[188:191], v[36:39]
	v_mfma_f32_16x16x32_bf16 v[24:27], v[148:151], v[196:199], v[24:27]
	v_mfma_f32_16x16x32_bf16 v[20:23], v[156:159], v[196:199], v[20:23]
	v_mfma_f32_16x16x32_bf16 v[8:11], v[148:151], v[204:207], v[8:11]
	v_mfma_f32_16x16x32_bf16 v[4:7], v[156:159], v[204:207], v[4:7]
	v_mfma_f32_16x16x32_bf16 v[56:59], v[152:155], v[178:181], v[56:59]
	v_mfma_f32_16x16x32_bf16 v[52:55], v[170:173], v[178:181], v[52:55]
	v_mfma_f32_16x16x32_bf16 v[40:43], v[152:155], v[192:195], v[40:43]
	v_mfma_f32_16x16x32_bf16 v[36:39], v[170:173], v[192:195], v[36:39]
	v_mfma_f32_16x16x32_bf16 v[24:27], v[152:155], v[200:203], v[24:27]
	v_mfma_f32_16x16x32_bf16 v[20:23], v[170:173], v[200:203], v[20:23]
	v_mfma_f32_16x16x32_bf16 v[8:11], v[152:155], v[208:211], v[8:11]
	v_mfma_f32_16x16x32_bf16 v[4:7], v[170:173], v[208:211], v[4:7]
	s_barrier
	s_setprio 0
	s_add_i32 s81, 0, 0x18000
	s_add_i32 s83, 0, 0x1c000
	v_add_u32_e32 v144, s81, v182
	v_add_u32_e32 v170, s83, v182
	ds_read_b128 v[132:135], v144
	ds_read_b128 v[136:139], v144 offset:1024
	ds_read_b128 v[140:143], v144 offset:2048
	ds_read_b128 v[144:147], v144 offset:3072
	ds_read_b128 v[148:151], v170
	ds_read_b128 v[152:155], v170 offset:1024
	ds_read_b128 v[156:159], v170 offset:2048
	ds_read_b128 v[170:173], v170 offset:3072
	s_add_u32 s36, s36, 0x80000
	s_addc_u32 s37, s37, 0
	s_mov_b32 m0, s39
	v_lshl_add_u64 v[228:229], s[36:37], 0, v[164:165]
	ds_read_b128 v[174:177], v186 offset:32768
	ds_read_b128 v[178:181], v186 offset:33792
	ds_read_b128 v[188:191], v186 offset:34816
	ds_read_b128 v[192:195], v186 offset:35840
	ds_read_b128 v[196:199], v186 offset:36864
	ds_read_b128 v[200:203], v186 offset:37888
	ds_read_b128 v[204:207], v186 offset:38912
	ds_read_b128 v[208:211], v186 offset:39936
	global_load_lds_dwordx4 v[228:229], off
	v_lshl_add_u64 v[228:229], s[36:37], 0, v[160:161]
	s_mov_b32 m0, s43
	s_nop 0
	global_load_lds_dwordx4 v[228:229], off
	s_waitcnt vmcnt(8)
	s_waitcnt lgkmcnt(0)
	s_setprio 1
	s_barrier
	v_mfma_f32_16x16x32_bf16 v[128:131], v[132:135], v[174:177], v[128:131]
	v_mfma_f32_16x16x32_bf16 v[124:127], v[140:143], v[174:177], v[124:127]
	v_mfma_f32_16x16x32_bf16 v[112:115], v[132:135], v[188:191], v[112:115]
	v_mfma_f32_16x16x32_bf16 v[108:111], v[140:143], v[188:191], v[108:111]
	v_mfma_f32_16x16x32_bf16 v[96:99], v[132:135], v[196:199], v[96:99]
	v_mfma_f32_16x16x32_bf16 v[92:95], v[140:143], v[196:199], v[92:95]
	v_mfma_f32_16x16x32_bf16 v[80:83], v[132:135], v[204:207], v[80:83]
	v_mfma_f32_16x16x32_bf16 v[76:79], v[140:143], v[204:207], v[76:79]
	v_mfma_f32_16x16x32_bf16 v[128:131], v[136:139], v[178:181], v[128:131]
	v_mfma_f32_16x16x32_bf16 v[124:127], v[144:147], v[178:181], v[124:127]
	v_mfma_f32_16x16x32_bf16 v[112:115], v[136:139], v[192:195], v[112:115]
	v_mfma_f32_16x16x32_bf16 v[108:111], v[144:147], v[192:195], v[108:111]
	v_mfma_f32_16x16x32_bf16 v[96:99], v[136:139], v[200:203], v[96:99]
	v_mfma_f32_16x16x32_bf16 v[92:95], v[144:147], v[200:203], v[92:95]
	v_mfma_f32_16x16x32_bf16 v[80:83], v[136:139], v[208:211], v[80:83]
	v_mfma_f32_16x16x32_bf16 v[76:79], v[144:147], v[208:211], v[76:79]
	s_setprio 0
	s_setprio 1
	v_mfma_f32_16x16x32_bf16 v[120:123], v[148:151], v[174:177], v[120:123]
	v_mfma_f32_16x16x32_bf16 v[116:119], v[156:159], v[174:177], v[116:119]
	v_mfma_f32_16x16x32_bf16 v[104:107], v[148:151], v[188:191], v[104:107]
	v_mfma_f32_16x16x32_bf16 v[100:103], v[156:159], v[188:191], v[100:103]
	v_mfma_f32_16x16x32_bf16 v[88:91], v[148:151], v[196:199], v[88:91]
	v_mfma_f32_16x16x32_bf16 v[84:87], v[156:159], v[196:199], v[84:87]
	v_mfma_f32_16x16x32_bf16 v[72:75], v[148:151], v[204:207], v[72:75]
	v_mfma_f32_16x16x32_bf16 v[68:71], v[156:159], v[204:207], v[68:71]
	v_mfma_f32_16x16x32_bf16 v[120:123], v[152:155], v[178:181], v[120:123]
	v_mfma_f32_16x16x32_bf16 v[116:119], v[170:173], v[178:181], v[116:119]
	v_mfma_f32_16x16x32_bf16 v[104:107], v[152:155], v[192:195], v[104:107]
	v_mfma_f32_16x16x32_bf16 v[100:103], v[170:173], v[192:195], v[100:103]
	v_mfma_f32_16x16x32_bf16 v[88:91], v[152:155], v[200:203], v[88:91]
	v_mfma_f32_16x16x32_bf16 v[84:87], v[170:173], v[200:203], v[84:87]
	v_mfma_f32_16x16x32_bf16 v[72:75], v[152:155], v[208:211], v[72:75]
	v_mfma_f32_16x16x32_bf16 v[68:71], v[170:173], v[208:211], v[68:71]
	s_barrier
	s_setprio 0
	s_add_i32 s36, s81, s0
	v_lshl_add_u64 v[212:213], v[212:213], 0, s[70:71]
	s_mov_b32 m0, s36
	ds_read_b128 v[174:177], v186 offset:49152
	ds_read_b128 v[178:181], v186 offset:50176
	ds_read_b128 v[188:191], v186 offset:51200
	ds_read_b128 v[192:195], v186 offset:52224
	ds_read_b128 v[196:199], v186 offset:53248
	ds_read_b128 v[200:203], v186 offset:54272
	ds_read_b128 v[204:207], v186 offset:55296
	ds_read_b128 v[208:211], v186 offset:56320
	global_load_lds_dwordx4 v[212:213], off
	s_add_i32 m0, s36, 0x2000
	s_add_u32 s34, s34, 0x80080
	v_lshl_add_u64 v[212:213], v[214:215], 0, s[70:71]
	s_addc_u32 s35, s35, 0
	s_add_i32 s36, s83, s0
	global_load_lds_dwordx4 v[212:213], off
	v_lshl_add_u64 v[212:213], s[34:35], 0, v[162:163]
	s_mov_b32 m0, s36
	s_nop 0
	global_load_lds_dwordx4 v[212:213], off
	v_lshl_add_u64 v[212:213], s[34:35], 0, v[0:1]
	s_add_i32 m0, s36, 0x2000
	s_nop 0
	global_load_lds_dwordx4 v[212:213], off
	v_lshl_add_u64 v[212:213], v[216:217], 0, s[70:71]
	s_mov_b32 m0, s47
	s_nop 0
	global_load_lds_dwordx4 v[212:213], off
	v_lshl_add_u64 v[212:213], v[226:227], 0, s[70:71]
	s_mov_b32 m0, s51
	s_nop 0
	global_load_lds_dwordx4 v[212:213], off
	s_waitcnt vmcnt(8)
	s_waitcnt lgkmcnt(0)
	s_setprio 1
	s_barrier
	v_mfma_f32_16x16x32_bf16 v[64:67], v[132:135], v[174:177], v[64:67]
	v_mfma_f32_16x16x32_bf16 v[60:63], v[140:143], v[174:177], v[60:63]
	v_mfma_f32_16x16x32_bf16 v[48:51], v[132:135], v[188:191], v[48:51]
	v_mfma_f32_16x16x32_bf16 v[44:47], v[140:143], v[188:191], v[44:47]
	v_mfma_f32_16x16x32_bf16 v[32:35], v[132:135], v[196:199], v[32:35]
	v_mfma_f32_16x16x32_bf16 v[28:31], v[140:143], v[196:199], v[28:31]
	v_mfma_f32_16x16x32_bf16 v[16:19], v[132:135], v[204:207], v[16:19]
	v_mfma_f32_16x16x32_bf16 v[12:15], v[140:143], v[204:207], v[12:15]
	v_mfma_f32_16x16x32_bf16 v[64:67], v[136:139], v[178:181], v[64:67]
	v_mfma_f32_16x16x32_bf16 v[60:63], v[144:147], v[178:181], v[60:63]
	v_mfma_f32_16x16x32_bf16 v[48:51], v[136:139], v[192:195], v[48:51]
	v_mfma_f32_16x16x32_bf16 v[44:47], v[144:147], v[192:195], v[44:47]
	v_mfma_f32_16x16x32_bf16 v[32:35], v[136:139], v[200:203], v[32:35]
	v_mfma_f32_16x16x32_bf16 v[28:31], v[144:147], v[200:203], v[28:31]
	v_mfma_f32_16x16x32_bf16 v[16:19], v[136:139], v[208:211], v[16:19]
	v_mfma_f32_16x16x32_bf16 v[12:15], v[144:147], v[208:211], v[12:15]
	s_setprio 0
	s_setprio 1
	v_mfma_f32_16x16x32_bf16 v[56:59], v[148:151], v[174:177], v[56:59]
	v_mfma_f32_16x16x32_bf16 v[52:55], v[156:159], v[174:177], v[52:55]
	v_mfma_f32_16x16x32_bf16 v[40:43], v[148:151], v[188:191], v[40:43]
	v_mfma_f32_16x16x32_bf16 v[36:39], v[156:159], v[188:191], v[36:39]
	v_mfma_f32_16x16x32_bf16 v[24:27], v[148:151], v[196:199], v[24:27]
	v_mfma_f32_16x16x32_bf16 v[20:23], v[156:159], v[196:199], v[20:23]
	v_mfma_f32_16x16x32_bf16 v[8:11], v[148:151], v[204:207], v[8:11]
	v_mfma_f32_16x16x32_bf16 v[4:7], v[156:159], v[204:207], v[4:7]
	v_mfma_f32_16x16x32_bf16 v[56:59], v[152:155], v[178:181], v[56:59]
	v_mfma_f32_16x16x32_bf16 v[52:55], v[170:173], v[178:181], v[52:55]
	v_mfma_f32_16x16x32_bf16 v[40:43], v[152:155], v[192:195], v[40:43]
	v_mfma_f32_16x16x32_bf16 v[36:39], v[170:173], v[192:195], v[36:39]
	v_mfma_f32_16x16x32_bf16 v[24:27], v[152:155], v[200:203], v[24:27]
	v_mfma_f32_16x16x32_bf16 v[20:23], v[170:173], v[200:203], v[20:23]
	v_mfma_f32_16x16x32_bf16 v[8:11], v[152:155], v[208:211], v[8:11]
	v_mfma_f32_16x16x32_bf16 v[4:7], v[170:173], v[208:211], v[4:7]
	s_barrier
	s_setprio 0
	s_add_i32 s75, s75, 2
	s_add_u32 s30, s30, 0x100
	s_addc_u32 s31, s31, 0
	s_add_u32 s69, s69, 0x100
	s_addc_u32 s74, s74, 0
	s_cmp_gt_u32 s75, 29
	s_cbranch_scc0 .LBB0_975
	s_and_b64 vcc, exec, s[20:21]
	s_cbranch_vccz .LBB0_978
	s_barrier

.LBB0_1067:
	s_add_u32 s34, s26, s12
	s_addc_u32 s35, s27, s13
	s_add_u32 s34, s34, 0x100
	s_addc_u32 s35, s35, 0
	s_add_u32 s83, s42, s12
	s_addc_u32 s92, s75, s13
	s_add_i32 s93, 0, 0x10000
	s_cmpk_eq_i32 s12, 0xf00
	s_cselect_b32 s37, s25, s35
	s_cselect_b32 s36, s81, s34
	s_cselect_b32 s35, s23, s92
	s_cselect_b32 s34, s84, s83
	s_add_i32 s83, 0, 0x14000
	v_add_u32_e32 v148, s93, v189
	v_add_u32_e32 v176, s83, v189
	ds_read_b128 v[136:139], v148
	ds_read_b128 v[140:143], v148 offset:1024
	ds_read_b128 v[144:147], v148 offset:2048
	ds_read_b128 v[148:151], v148 offset:3072
	ds_read_b128 v[152:155], v176
	ds_read_b128 v[156:159], v176 offset:1024
	ds_read_b128 v[160:163], v176 offset:2048
	ds_read_b128 v[176:179], v176 offset:3072
	v_lshl_add_u64 v[184:185], v[132:133], 0, s[12:13]
	s_add_i32 m0, s39, 0xc000
	ds_read_b128 v[180:183], v192
	ds_read_b128 v[194:197], v192 offset:1024
	ds_read_b128 v[198:201], v192 offset:2048
	ds_read_b128 v[202:205], v192 offset:3072
	ds_read_b128 v[206:209], v192 offset:4096
	ds_read_b128 v[210:213], v192 offset:5120
	ds_read_b128 v[214:217], v192 offset:6144
	ds_read_b128 v[226:229], v192 offset:7168
	global_load_lds_dwordx4 v[184:185], off
	v_lshl_add_u64 v[184:185], v[134:135], 0, s[12:13]
	s_add_i32 m0, s39, 0xe000
	s_nop 0
	global_load_lds_dwordx4 v[184:185], off
	s_waitcnt vmcnt(8)
	s_waitcnt lgkmcnt(0)
	s_setprio 1
	s_barrier
	v_mfma_f32_16x16x32_bf16 v[8:11], v[136:139], v[180:183], v[8:11]
	v_mfma_f32_16x16x32_bf16 v[128:131], v[144:147], v[180:183], v[128:131]
	v_mfma_f32_16x16x32_bf16 v[124:127], v[136:139], v[198:201], v[124:127]
	v_mfma_f32_16x16x32_bf16 v[120:123], v[144:147], v[198:201], v[120:123]
	v_mfma_f32_16x16x32_bf16 v[116:119], v[136:139], v[206:209], v[116:119]
	v_mfma_f32_16x16x32_bf16 v[112:115], v[144:147], v[206:209], v[112:115]
	v_mfma_f32_16x16x32_bf16 v[108:111], v[136:139], v[214:217], v[108:111]
	v_mfma_f32_16x16x32_bf16 v[104:107], v[144:147], v[214:217], v[104:107]
	v_mfma_f32_16x16x32_bf16 v[8:11], v[140:143], v[194:197], v[8:11]
	v_mfma_f32_16x16x32_bf16 v[128:131], v[148:151], v[194:197], v[128:131]
	v_mfma_f32_16x16x32_bf16 v[124:127], v[140:143], v[202:205], v[124:127]
	v_mfma_f32_16x16x32_bf16 v[120:123], v[148:151], v[202:205], v[120:123]
	v_mfma_f32_16x16x32_bf16 v[116:119], v[140:143], v[210:213], v[116:119]
	v_mfma_f32_16x16x32_bf16 v[112:115], v[148:151], v[210:213], v[112:115]
	v_mfma_f32_16x16x32_bf16 v[108:111], v[140:143], v[226:229], v[108:111]
	v_mfma_f32_16x16x32_bf16 v[104:107], v[148:151], v[226:229], v[104:107]
	s_setprio 0
	s_setprio 1
	v_mfma_f32_16x16x32_bf16 v[100:103], v[152:155], v[180:183], v[100:103]
	v_mfma_f32_16x16x32_bf16 v[96:99], v[160:163], v[180:183], v[96:99]
	v_mfma_f32_16x16x32_bf16 v[92:95], v[152:155], v[198:201], v[92:95]
	v_mfma_f32_16x16x32_bf16 v[88:91], v[160:163], v[198:201], v[88:91]
	v_mfma_f32_16x16x32_bf16 v[84:87], v[152:155], v[206:209], v[84:87]
	v_mfma_f32_16x16x32_bf16 v[80:83], v[160:163], v[206:209], v[80:83]
	v_mfma_f32_16x16x32_bf16 v[76:79], v[152:155], v[214:217], v[76:79]
	v_mfma_f32_16x16x32_bf16 v[72:75], v[160:163], v[214:217], v[72:75]
	v_mfma_f32_16x16x32_bf16 v[100:103], v[156:159], v[194:197], v[100:103]
	v_mfma_f32_16x16x32_bf16 v[96:99], v[176:179], v[194:197], v[96:99]
	v_mfma_f32_16x16x32_bf16 v[92:95], v[156:159], v[202:205], v[92:95]
	v_mfma_f32_16x16x32_bf16 v[88:91], v[176:179], v[202:205], v[88:91]
	v_mfma_f32_16x16x32_bf16 v[84:87], v[156:159], v[210:213], v[84:87]
	v_mfma_f32_16x16x32_bf16 v[80:83], v[176:179], v[210:213], v[80:83]
	v_mfma_f32_16x16x32_bf16 v[76:79], v[156:159], v[226:229], v[76:79]
	v_mfma_f32_16x16x32_bf16 v[72:75], v[176:179], v[226:229], v[72:75]
	s_barrier
	s_setprio 0
	s_add_i32 s92, s93, s38
	v_lshl_add_u64 v[184:185], s[34:35], 0, v[164:165]
	s_mov_b32 m0, s92
	ds_read_b128 v[180:183], v192 offset:16384
	ds_read_b128 v[194:197], v192 offset:17408
	ds_read_b128 v[198:201], v192 offset:18432
	ds_read_b128 v[202:205], v192 offset:19456
	ds_read_b128 v[206:209], v192 offset:20480
	ds_read_b128 v[210:213], v192 offset:21504
	ds_read_b128 v[214:217], v192 offset:22528
	ds_read_b128 v[226:229], v192 offset:23552
	global_load_lds_dwordx4 v[184:185], off
	s_add_i32 m0, s92, 0x2000
	s_add_u32 s92, s34, 0x80000
	v_lshl_add_u64 v[230:231], s[34:35], 0, v[168:169]
	s_addc_u32 s93, s35, 0
	s_add_i32 s83, s83, s38
	global_load_lds_dwordx4 v[230:231], off
	v_lshl_add_u64 v[232:233], s[92:93], 0, v[164:165]
	s_mov_b32 m0, s83
	v_lshl_add_u64 v[234:235], s[36:37], 0, v[166:167]
	global_load_lds_dwordx4 v[232:233], off
	v_lshl_add_u64 v[232:233], s[92:93], 0, v[168:169]
	s_add_i32 m0, s83, 0x2000
	s_nop 0
	global_load_lds_dwordx4 v[232:233], off
	v_lshl_add_u64 v[232:233], s[36:37], 0, v[0:1]
	s_mov_b32 m0, s39
	s_nop 0
	global_load_lds_dwordx4 v[232:233], off
	s_mov_b32 m0, s43
	s_nop 0
	global_load_lds_dwordx4 v[234:235], off
	s_waitcnt vmcnt(8)
	s_waitcnt lgkmcnt(0)
	s_setprio 1
	s_barrier
	v_mfma_f32_16x16x32_bf16 v[68:71], v[136:139], v[180:183], v[68:71]
	v_mfma_f32_16x16x32_bf16 v[64:67], v[144:147], v[180:183], v[64:67]
	v_mfma_f32_16x16x32_bf16 v[60:63], v[136:139], v[198:201], v[60:63]
	v_mfma_f32_16x16x32_bf16 v[56:59], v[144:147], v[198:201], v[56:59]
	v_mfma_f32_16x16x32_bf16 v[52:55], v[136:139], v[206:209], v[52:55]
	v_mfma_f32_16x16x32_bf16 v[48:51], v[144:147], v[206:209], v[48:51]
	v_mfma_f32_16x16x32_bf16 v[44:47], v[136:139], v[214:217], v[44:47]
	v_mfma_f32_16x16x32_bf16 v[40:43], v[144:147], v[214:217], v[40:43]
	v_mfma_f32_16x16x32_bf16 v[68:71], v[140:143], v[194:197], v[68:71]
	v_mfma_f32_16x16x32_bf16 v[64:67], v[148:151], v[194:197], v[64:67]
	v_mfma_f32_16x16x32_bf16 v[60:63], v[140:143], v[202:205], v[60:63]
	v_mfma_f32_16x16x32_bf16 v[56:59], v[148:151], v[202:205], v[56:59]
	v_mfma_f32_16x16x32_bf16 v[52:55], v[140:143], v[210:213], v[52:55]
	v_mfma_f32_16x16x32_bf16 v[48:51], v[148:151], v[210:213], v[48:51]
	v_mfma_f32_16x16x32_bf16 v[44:47], v[140:143], v[226:229], v[44:47]
	v_mfma_f32_16x16x32_bf16 v[40:43], v[148:151], v[226:229], v[40:43]
	s_setprio 0
	s_setprio 1
	v_mfma_f32_16x16x32_bf16 v[36:39], v[152:155], v[180:183], v[36:39]
	v_mfma_f32_16x16x32_bf16 v[32:35], v[160:163], v[180:183], v[32:35]
	v_mfma_f32_16x16x32_bf16 v[28:31], v[152:155], v[198:201], v[28:31]
	v_mfma_f32_16x16x32_bf16 v[24:27], v[160:163], v[198:201], v[24:27]
	v_mfma_f32_16x16x32_bf16 v[20:23], v[152:155], v[206:209], v[20:23]
	v_mfma_f32_16x16x32_bf16 v[16:19], v[160:163], v[206:209], v[16:19]
	v_mfma_f32_16x16x32_bf16 v[12:15], v[152:155], v[214:217], v[12:15]
	v_mfma_f32_16x16x32_bf16 v[4:7], v[160:163], v[214:217], v[4:7]
	v_mfma_f32_16x16x32_bf16 v[36:39], v[156:159], v[194:197], v[36:39]
	v_mfma_f32_16x16x32_bf16 v[32:35], v[176:179], v[194:197], v[32:35]
	v_mfma_f32_16x16x32_bf16 v[28:31], v[156:159], v[202:205], v[28:31]
	v_mfma_f32_16x16x32_bf16 v[24:27], v[176:179], v[202:205], v[24:27]
	v_mfma_f32_16x16x32_bf16 v[20:23], v[156:159], v[210:213], v[20:23]
	v_mfma_f32_16x16x32_bf16 v[16:19], v[176:179], v[210:213], v[16:19]
	v_mfma_f32_16x16x32_bf16 v[12:15], v[156:159], v[226:229], v[12:15]
	v_mfma_f32_16x16x32_bf16 v[4:7], v[176:179], v[226:229], v[4:7]
	s_barrier
	s_setprio 0
	s_add_i32 s83, 0, 0x18000
	s_add_i32 s92, 0, 0x1c000
	v_add_u32_e32 v148, s83, v189
	v_add_u32_e32 v176, s92, v189
	ds_read_b128 v[136:139], v148
	ds_read_b128 v[140:143], v148 offset:1024
	ds_read_b128 v[144:147], v148 offset:2048
	ds_read_b128 v[148:151], v148 offset:3072
	ds_read_b128 v[152:155], v176
	ds_read_b128 v[156:159], v176 offset:1024
	ds_read_b128 v[160:163], v176 offset:2048
	ds_read_b128 v[176:179], v176 offset:3072
	s_add_u32 s36, s36, 0x80000
	s_addc_u32 s37, s37, 0
	s_mov_b32 m0, s46
	v_lshl_add_u64 v[236:237], s[36:37], 0, v[0:1]
	ds_read_b128 v[180:183], v192 offset:32768
	ds_read_b128 v[194:197], v192 offset:33792
	ds_read_b128 v[198:201], v192 offset:34816
	ds_read_b128 v[202:205], v192 offset:35840
	ds_read_b128 v[206:209], v192 offset:36864
	ds_read_b128 v[210:213], v192 offset:37888
	ds_read_b128 v[214:217], v192 offset:38912
	ds_read_b128 v[226:229], v192 offset:39936
	global_load_lds_dwordx4 v[236:237], off
	v_lshl_add_u64 v[236:237], s[36:37], 0, v[166:167]
	s_mov_b32 m0, s47
	s_nop 0
	global_load_lds_dwordx4 v[236:237], off
	s_waitcnt vmcnt(8)
	s_waitcnt lgkmcnt(0)
	s_setprio 1
	s_barrier
	v_mfma_f32_16x16x32_bf16 v[8:11], v[136:139], v[180:183], v[8:11]
	v_mfma_f32_16x16x32_bf16 v[128:131], v[144:147], v[180:183], v[128:131]
	v_mfma_f32_16x16x32_bf16 v[124:127], v[136:139], v[198:201], v[124:127]
	v_mfma_f32_16x16x32_bf16 v[120:123], v[144:147], v[198:201], v[120:123]
	v_mfma_f32_16x16x32_bf16 v[116:119], v[136:139], v[206:209], v[116:119]
	v_mfma_f32_16x16x32_bf16 v[112:115], v[144:147], v[206:209], v[112:115]
	v_mfma_f32_16x16x32_bf16 v[108:111], v[136:139], v[214:217], v[108:111]
	v_mfma_f32_16x16x32_bf16 v[104:107], v[144:147], v[214:217], v[104:107]
	v_mfma_f32_16x16x32_bf16 v[8:11], v[140:143], v[194:197], v[8:11]
	v_mfma_f32_16x16x32_bf16 v[128:131], v[148:151], v[194:197], v[128:131]
	v_mfma_f32_16x16x32_bf16 v[124:127], v[140:143], v[202:205], v[124:127]
	v_mfma_f32_16x16x32_bf16 v[120:123], v[148:151], v[202:205], v[120:123]
	v_mfma_f32_16x16x32_bf16 v[116:119], v[140:143], v[210:213], v[116:119]
	v_mfma_f32_16x16x32_bf16 v[112:115], v[148:151], v[210:213], v[112:115]
	v_mfma_f32_16x16x32_bf16 v[108:111], v[140:143], v[226:229], v[108:111]
	v_mfma_f32_16x16x32_bf16 v[104:107], v[148:151], v[226:229], v[104:107]
	s_setprio 0
	s_setprio 1
	v_mfma_f32_16x16x32_bf16 v[100:103], v[152:155], v[180:183], v[100:103]
	v_mfma_f32_16x16x32_bf16 v[96:99], v[160:163], v[180:183], v[96:99]
	v_mfma_f32_16x16x32_bf16 v[92:95], v[152:155], v[198:201], v[92:95]
	v_mfma_f32_16x16x32_bf16 v[88:91], v[160:163], v[198:201], v[88:91]
	v_mfma_f32_16x16x32_bf16 v[84:87], v[152:155], v[206:209], v[84:87]
	v_mfma_f32_16x16x32_bf16 v[80:83], v[160:163], v[206:209], v[80:83]
	v_mfma_f32_16x16x32_bf16 v[76:79], v[152:155], v[214:217], v[76:79]
	v_mfma_f32_16x16x32_bf16 v[72:75], v[160:163], v[214:217], v[72:75]
	v_mfma_f32_16x16x32_bf16 v[100:103], v[156:159], v[194:197], v[100:103]
	v_mfma_f32_16x16x32_bf16 v[96:99], v[176:179], v[194:197], v[96:99]
	v_mfma_f32_16x16x32_bf16 v[92:95], v[156:159], v[202:205], v[92:95]
	v_mfma_f32_16x16x32_bf16 v[88:91], v[176:179], v[202:205], v[88:91]
	v_mfma_f32_16x16x32_bf16 v[84:87], v[156:159], v[210:213], v[84:87]
	v_mfma_f32_16x16x32_bf16 v[80:83], v[176:179], v[210:213], v[80:83]
	v_mfma_f32_16x16x32_bf16 v[76:79], v[156:159], v[226:229], v[76:79]
	v_mfma_f32_16x16x32_bf16 v[72:75], v[176:179], v[226:229], v[72:75]
	s_barrier
	s_setprio 0
	s_add_i32 s36, s83, s38
	v_lshl_add_u64 v[184:185], v[184:185], 0, s[70:71]
	s_mov_b32 m0, s36
	ds_read_b128 v[180:183], v192 offset:49152
	ds_read_b128 v[194:197], v192 offset:50176
	ds_read_b128 v[198:201], v192 offset:51200
	ds_read_b128 v[202:205], v192 offset:52224
	ds_read_b128 v[206:209], v192 offset:53248
	ds_read_b128 v[210:213], v192 offset:54272
	ds_read_b128 v[214:217], v192 offset:55296
	ds_read_b128 v[226:229], v192 offset:56320
	global_load_lds_dwordx4 v[184:185], off
	s_add_i32 m0, s36, 0x2000
	s_add_u32 s34, s34, 0x80080
	v_lshl_add_u64 v[184:185], v[230:231], 0, s[70:71]
	s_addc_u32 s35, s35, 0
	s_add_i32 s36, s92, s38
	global_load_lds_dwordx4 v[184:185], off
	v_lshl_add_u64 v[184:185], s[34:35], 0, v[164:165]
	s_mov_b32 m0, s36
	s_nop 0
	global_load_lds_dwordx4 v[184:185], off
	v_lshl_add_u64 v[184:185], s[34:35], 0, v[168:169]
	s_add_i32 m0, s36, 0x2000
	s_nop 0
	global_load_lds_dwordx4 v[184:185], off
	v_lshl_add_u64 v[184:185], v[232:233], 0, s[70:71]
	s_mov_b32 m0, s51
	s_nop 0
	global_load_lds_dwordx4 v[184:185], off
	v_lshl_add_u64 v[184:185], v[234:235], 0, s[70:71]
	s_mov_b32 m0, s52
	s_nop 0
	global_load_lds_dwordx4 v[184:185], off
	s_waitcnt vmcnt(8)
	s_waitcnt lgkmcnt(0)
	s_setprio 1
	s_barrier
	v_mfma_f32_16x16x32_bf16 v[68:71], v[136:139], v[180:183], v[68:71]
	v_mfma_f32_16x16x32_bf16 v[64:67], v[144:147], v[180:183], v[64:67]
	v_mfma_f32_16x16x32_bf16 v[60:63], v[136:139], v[198:201], v[60:63]
	v_mfma_f32_16x16x32_bf16 v[56:59], v[144:147], v[198:201], v[56:59]
	v_mfma_f32_16x16x32_bf16 v[52:55], v[136:139], v[206:209], v[52:55]
	v_mfma_f32_16x16x32_bf16 v[48:51], v[144:147], v[206:209], v[48:51]
	v_mfma_f32_16x16x32_bf16 v[44:47], v[136:139], v[214:217], v[44:47]
	v_mfma_f32_16x16x32_bf16 v[40:43], v[144:147], v[214:217], v[40:43]
	v_mfma_f32_16x16x32_bf16 v[68:71], v[140:143], v[194:197], v[68:71]
	v_mfma_f32_16x16x32_bf16 v[64:67], v[148:151], v[194:197], v[64:67]
	v_mfma_f32_16x16x32_bf16 v[60:63], v[140:143], v[202:205], v[60:63]
	v_mfma_f32_16x16x32_bf16 v[56:59], v[148:151], v[202:205], v[56:59]
	v_mfma_f32_16x16x32_bf16 v[52:55], v[140:143], v[210:213], v[52:55]
	v_mfma_f32_16x16x32_bf16 v[48:51], v[148:151], v[210:213], v[48:51]
	v_mfma_f32_16x16x32_bf16 v[44:47], v[140:143], v[226:229], v[44:47]
	v_mfma_f32_16x16x32_bf16 v[40:43], v[148:151], v[226:229], v[40:43]
	s_setprio 0
	s_setprio 1
	v_mfma_f32_16x16x32_bf16 v[36:39], v[152:155], v[180:183], v[36:39]
	v_mfma_f32_16x16x32_bf16 v[32:35], v[160:163], v[180:183], v[32:35]
	v_mfma_f32_16x16x32_bf16 v[28:31], v[152:155], v[198:201], v[28:31]
	v_mfma_f32_16x16x32_bf16 v[24:27], v[160:163], v[198:201], v[24:27]
	v_mfma_f32_16x16x32_bf16 v[20:23], v[152:155], v[206:209], v[20:23]
	v_mfma_f32_16x16x32_bf16 v[16:19], v[160:163], v[206:209], v[16:19]
	v_mfma_f32_16x16x32_bf16 v[12:15], v[152:155], v[214:217], v[12:15]
	v_mfma_f32_16x16x32_bf16 v[4:7], v[160:163], v[214:217], v[4:7]
	v_mfma_f32_16x16x32_bf16 v[36:39], v[156:159], v[194:197], v[36:39]
	v_mfma_f32_16x16x32_bf16 v[32:35], v[176:179], v[194:197], v[32:35]
	v_mfma_f32_16x16x32_bf16 v[28:31], v[156:159], v[202:205], v[28:31]
	v_mfma_f32_16x16x32_bf16 v[24:27], v[176:179], v[202:205], v[24:27]
	v_mfma_f32_16x16x32_bf16 v[20:23], v[156:159], v[210:213], v[20:23]
	v_mfma_f32_16x16x32_bf16 v[16:19], v[176:179], v[210:213], v[16:19]
	v_mfma_f32_16x16x32_bf16 v[12:15], v[156:159], v[226:229], v[12:15]
	v_mfma_f32_16x16x32_bf16 v[4:7], v[176:179], v[226:229], v[4:7]
	s_barrier
	s_setprio 0
	s_add_i32 s85, s85, 2
	s_add_u32 s12, s12, 0x100
	s_addc_u32 s13, s13, 0
	s_cmp_gt_u32 s85, 29
	s_cbranch_scc0 .LBB0_1067
	s_and_b64 vcc, exec, s[20:21]
	s_cbranch_vccz .LBB0_1070
	s_barrier

.LBB0_1205:
	s_add_u32 s24, s22, 0x100
	s_addc_u32 s25, s23, 0
	s_add_i32 s67, 0, 0x10000
	s_cmpk_eq_i32 s66, 0x54
	s_cselect_b32 s29, s9, s25
	s_cselect_b32 s28, s8, s24
	s_cselect_b32 s27, s21, s54
	s_cselect_b32 s26, s20, s52
	s_add_i32 s69, 0, 0x14000
	v_add_u32_e32 v144, s67, v182
	v_add_u32_e32 v170, s69, v182
	ds_read_b128 v[132:135], v144
	ds_read_b128 v[136:139], v144 offset:1024
	ds_read_b128 v[140:143], v144 offset:2048
	ds_read_b128 v[144:147], v144 offset:3072
	ds_read_b128 v[148:151], v170
	ds_read_b128 v[152:155], v170 offset:1024
	ds_read_b128 v[156:159], v170 offset:2048
	ds_read_b128 v[170:173], v170 offset:3072
	v_lshl_add_u64 v[212:213], s[22:23], 0, v[166:167]
	s_add_i32 m0, s31, 0xc000
	ds_read_b128 v[174:177], v186
	ds_read_b128 v[178:181], v186 offset:1024
	ds_read_b128 v[188:191], v186 offset:2048
	ds_read_b128 v[192:195], v186 offset:3072
	ds_read_b128 v[196:199], v186 offset:4096
	ds_read_b128 v[200:203], v186 offset:5120
	ds_read_b128 v[204:207], v186 offset:6144
	ds_read_b128 v[208:211], v186 offset:7168
	global_load_lds_dwordx4 v[212:213], off
	v_lshl_add_u64 v[212:213], s[22:23], 0, v[168:169]
	s_add_i32 m0, s31, 0xe000
	s_nop 0
	global_load_lds_dwordx4 v[212:213], off
	s_waitcnt vmcnt(8)
	s_waitcnt lgkmcnt(0)
	s_setprio 1
	s_barrier
	v_mfma_f32_16x16x32_bf16 v[128:131], v[132:135], v[174:177], v[128:131]
	v_mfma_f32_16x16x32_bf16 v[124:127], v[140:143], v[174:177], v[124:127]
	v_mfma_f32_16x16x32_bf16 v[112:115], v[132:135], v[188:191], v[112:115]
	v_mfma_f32_16x16x32_bf16 v[108:111], v[140:143], v[188:191], v[108:111]
	v_mfma_f32_16x16x32_bf16 v[96:99], v[132:135], v[196:199], v[96:99]
	v_mfma_f32_16x16x32_bf16 v[92:95], v[140:143], v[196:199], v[92:95]
	v_mfma_f32_16x16x32_bf16 v[80:83], v[132:135], v[204:207], v[80:83]
	v_mfma_f32_16x16x32_bf16 v[76:79], v[140:143], v[204:207], v[76:79]
	v_mfma_f32_16x16x32_bf16 v[128:131], v[136:139], v[178:181], v[128:131]
	v_mfma_f32_16x16x32_bf16 v[124:127], v[144:147], v[178:181], v[124:127]
	v_mfma_f32_16x16x32_bf16 v[112:115], v[136:139], v[192:195], v[112:115]
	v_mfma_f32_16x16x32_bf16 v[108:111], v[144:147], v[192:195], v[108:111]
	v_mfma_f32_16x16x32_bf16 v[96:99], v[136:139], v[200:203], v[96:99]
	v_mfma_f32_16x16x32_bf16 v[92:95], v[144:147], v[200:203], v[92:95]
	v_mfma_f32_16x16x32_bf16 v[80:83], v[136:139], v[208:211], v[80:83]
	v_mfma_f32_16x16x32_bf16 v[76:79], v[144:147], v[208:211], v[76:79]
	s_setprio 0
	s_setprio 1
	v_mfma_f32_16x16x32_bf16 v[120:123], v[148:151], v[174:177], v[120:123]
	v_mfma_f32_16x16x32_bf16 v[116:119], v[156:159], v[174:177], v[116:119]
	v_mfma_f32_16x16x32_bf16 v[104:107], v[148:151], v[188:191], v[104:107]
	v_mfma_f32_16x16x32_bf16 v[100:103], v[156:159], v[188:191], v[100:103]
	v_mfma_f32_16x16x32_bf16 v[88:91], v[148:151], v[196:199], v[88:91]
	v_mfma_f32_16x16x32_bf16 v[84:87], v[156:159], v[196:199], v[84:87]
	v_mfma_f32_16x16x32_bf16 v[72:75], v[148:151], v[204:207], v[72:75]
	v_mfma_f32_16x16x32_bf16 v[68:71], v[156:159], v[204:207], v[68:71]
	v_mfma_f32_16x16x32_bf16 v[120:123], v[152:155], v[178:181], v[120:123]
	v_mfma_f32_16x16x32_bf16 v[116:119], v[170:173], v[178:181], v[116:119]
	v_mfma_f32_16x16x32_bf16 v[104:107], v[152:155], v[192:195], v[104:107]
	v_mfma_f32_16x16x32_bf16 v[100:103], v[170:173], v[192:195], v[100:103]
	v_mfma_f32_16x16x32_bf16 v[88:91], v[152:155], v[200:203], v[88:91]
	v_mfma_f32_16x16x32_bf16 v[84:87], v[170:173], v[200:203], v[84:87]
	v_mfma_f32_16x16x32_bf16 v[72:75], v[152:155], v[208:211], v[72:75]
	v_mfma_f32_16x16x32_bf16 v[68:71], v[170:173], v[208:211], v[68:71]
	s_barrier
	s_setprio 0
	s_add_i32 s22, s67, s30
	v_lshl_add_u64 v[212:213], s[26:27], 0, v[162:163]
	s_mov_b32 m0, s22
	ds_read_b128 v[174:177], v186 offset:16384
	ds_read_b128 v[178:181], v186 offset:17408
	ds_read_b128 v[188:191], v186 offset:18432
	ds_read_b128 v[192:195], v186 offset:19456
	ds_read_b128 v[196:199], v186 offset:20480
	ds_read_b128 v[200:203], v186 offset:21504
	ds_read_b128 v[204:207], v186 offset:22528
	ds_read_b128 v[208:211], v186 offset:23552
	global_load_lds_dwordx4 v[212:213], off
	s_add_i32 m0, s22, 0x2000
	s_add_u32 s22, s26, 0x160000
	v_lshl_add_u64 v[214:215], s[26:27], 0, v[0:1]
	s_addc_u32 s23, s27, 0
	s_add_i32 s67, s69, s30
	global_load_lds_dwordx4 v[214:215], off
	v_lshl_add_u64 v[216:217], s[22:23], 0, v[162:163]
	s_mov_b32 m0, s67
	v_lshl_add_u64 v[226:227], s[28:29], 0, v[160:161]
	global_load_lds_dwordx4 v[216:217], off
	v_lshl_add_u64 v[216:217], s[22:23], 0, v[0:1]
	s_add_i32 m0, s67, 0x2000
	s_nop 0
	global_load_lds_dwordx4 v[216:217], off
	v_lshl_add_u64 v[216:217], s[28:29], 0, v[164:165]
	s_mov_b32 m0, s31
	s_nop 0
	global_load_lds_dwordx4 v[216:217], off
	s_mov_b32 m0, s34
	s_nop 0
	global_load_lds_dwordx4 v[226:227], off
	s_waitcnt vmcnt(8)
	s_waitcnt lgkmcnt(0)
	s_setprio 1
	s_barrier
	v_mfma_f32_16x16x32_bf16 v[64:67], v[132:135], v[174:177], v[64:67]
	v_mfma_f32_16x16x32_bf16 v[60:63], v[140:143], v[174:177], v[60:63]
	v_mfma_f32_16x16x32_bf16 v[48:51], v[132:135], v[188:191], v[48:51]
	v_mfma_f32_16x16x32_bf16 v[44:47], v[140:143], v[188:191], v[44:47]
	v_mfma_f32_16x16x32_bf16 v[32:35], v[132:135], v[196:199], v[32:35]
	v_mfma_f32_16x16x32_bf16 v[28:31], v[140:143], v[196:199], v[28:31]
	v_mfma_f32_16x16x32_bf16 v[16:19], v[132:135], v[204:207], v[16:19]
	v_mfma_f32_16x16x32_bf16 v[12:15], v[140:143], v[204:207], v[12:15]
	v_mfma_f32_16x16x32_bf16 v[64:67], v[136:139], v[178:181], v[64:67]
	v_mfma_f32_16x16x32_bf16 v[60:63], v[144:147], v[178:181], v[60:63]
	v_mfma_f32_16x16x32_bf16 v[48:51], v[136:139], v[192:195], v[48:51]
	v_mfma_f32_16x16x32_bf16 v[44:47], v[144:147], v[192:195], v[44:47]
	v_mfma_f32_16x16x32_bf16 v[32:35], v[136:139], v[200:203], v[32:35]
	v_mfma_f32_16x16x32_bf16 v[28:31], v[144:147], v[200:203], v[28:31]
	v_mfma_f32_16x16x32_bf16 v[16:19], v[136:139], v[208:211], v[16:19]
	v_mfma_f32_16x16x32_bf16 v[12:15], v[144:147], v[208:211], v[12:15]
	s_setprio 0
	s_setprio 1
	v_mfma_f32_16x16x32_bf16 v[56:59], v[148:151], v[174:177], v[56:59]
	v_mfma_f32_16x16x32_bf16 v[52:55], v[156:159], v[174:177], v[52:55]
	v_mfma_f32_16x16x32_bf16 v[40:43], v[148:151], v[188:191], v[40:43]
	v_mfma_f32_16x16x32_bf16 v[36:39], v[156:159], v[188:191], v[36:39]
	v_mfma_f32_16x16x32_bf16 v[24:27], v[148:151], v[196:199], v[24:27]
	v_mfma_f32_16x16x32_bf16 v[20:23], v[156:159], v[196:199], v[20:23]
	v_mfma_f32_16x16x32_bf16 v[8:11], v[148:151], v[204:207], v[8:11]
	v_mfma_f32_16x16x32_bf16 v[4:7], v[156:159], v[204:207], v[4:7]
	v_mfma_f32_16x16x32_bf16 v[56:59], v[152:155], v[178:181], v[56:59]
	v_mfma_f32_16x16x32_bf16 v[52:55], v[170:173], v[178:181], v[52:55]
	v_mfma_f32_16x16x32_bf16 v[40:43], v[152:155], v[192:195], v[40:43]
	v_mfma_f32_16x16x32_bf16 v[36:39], v[170:173], v[192:195], v[36:39]
	v_mfma_f32_16x16x32_bf16 v[24:27], v[152:155], v[200:203], v[24:27]
	v_mfma_f32_16x16x32_bf16 v[20:23], v[170:173], v[200:203], v[20:23]
	v_mfma_f32_16x16x32_bf16 v[8:11], v[152:155], v[208:211], v[8:11]
	v_mfma_f32_16x16x32_bf16 v[4:7], v[170:173], v[208:211], v[4:7]
	s_barrier
	s_setprio 0
	s_add_i32 s67, 0, 0x18000
	s_add_i32 s69, 0, 0x1c000
	v_add_u32_e32 v144, s67, v182
	v_add_u32_e32 v170, s69, v182
	ds_read_b128 v[132:135], v144
	ds_read_b128 v[136:139], v144 offset:1024
	ds_read_b128 v[140:143], v144 offset:2048
	ds_read_b128 v[144:147], v144 offset:3072
	ds_read_b128 v[148:151], v170
	ds_read_b128 v[152:155], v170 offset:1024
	ds_read_b128 v[156:159], v170 offset:2048
	ds_read_b128 v[170:173], v170 offset:3072
	s_add_u32 s22, s28, 0x160000
	s_addc_u32 s23, s29, 0
	s_mov_b32 m0, s35
	v_lshl_add_u64 v[228:229], s[22:23], 0, v[164:165]
	ds_read_b128 v[174:177], v186 offset:32768
	ds_read_b128 v[178:181], v186 offset:33792
	ds_read_b128 v[188:191], v186 offset:34816
	ds_read_b128 v[192:195], v186 offset:35840
	ds_read_b128 v[196:199], v186 offset:36864
	ds_read_b128 v[200:203], v186 offset:37888
	ds_read_b128 v[204:207], v186 offset:38912
	ds_read_b128 v[208:211], v186 offset:39936
	global_load_lds_dwordx4 v[228:229], off
	v_lshl_add_u64 v[228:229], s[22:23], 0, v[160:161]
	s_mov_b32 m0, s36
	s_nop 0
	global_load_lds_dwordx4 v[228:229], off
	s_waitcnt vmcnt(8)
	s_waitcnt lgkmcnt(0)
	s_setprio 1
	s_barrier
	v_mfma_f32_16x16x32_bf16 v[128:131], v[132:135], v[174:177], v[128:131]
	v_mfma_f32_16x16x32_bf16 v[124:127], v[140:143], v[174:177], v[124:127]
	v_mfma_f32_16x16x32_bf16 v[112:115], v[132:135], v[188:191], v[112:115]
	v_mfma_f32_16x16x32_bf16 v[108:111], v[140:143], v[188:191], v[108:111]
	v_mfma_f32_16x16x32_bf16 v[96:99], v[132:135], v[196:199], v[96:99]
	v_mfma_f32_16x16x32_bf16 v[92:95], v[140:143], v[196:199], v[92:95]
	v_mfma_f32_16x16x32_bf16 v[80:83], v[132:135], v[204:207], v[80:83]
	v_mfma_f32_16x16x32_bf16 v[76:79], v[140:143], v[204:207], v[76:79]
	v_mfma_f32_16x16x32_bf16 v[128:131], v[136:139], v[178:181], v[128:131]
	v_mfma_f32_16x16x32_bf16 v[124:127], v[144:147], v[178:181], v[124:127]
	v_mfma_f32_16x16x32_bf16 v[112:115], v[136:139], v[192:195], v[112:115]
	v_mfma_f32_16x16x32_bf16 v[108:111], v[144:147], v[192:195], v[108:111]
	v_mfma_f32_16x16x32_bf16 v[96:99], v[136:139], v[200:203], v[96:99]
	v_mfma_f32_16x16x32_bf16 v[92:95], v[144:147], v[200:203], v[92:95]
	v_mfma_f32_16x16x32_bf16 v[80:83], v[136:139], v[208:211], v[80:83]
	v_mfma_f32_16x16x32_bf16 v[76:79], v[144:147], v[208:211], v[76:79]
	s_setprio 0
	s_setprio 1
	v_mfma_f32_16x16x32_bf16 v[120:123], v[148:151], v[174:177], v[120:123]
	v_mfma_f32_16x16x32_bf16 v[116:119], v[156:159], v[174:177], v[116:119]
	v_mfma_f32_16x16x32_bf16 v[104:107], v[148:151], v[188:191], v[104:107]
	v_mfma_f32_16x16x32_bf16 v[100:103], v[156:159], v[188:191], v[100:103]
	v_mfma_f32_16x16x32_bf16 v[88:91], v[148:151], v[196:199], v[88:91]
	v_mfma_f32_16x16x32_bf16 v[84:87], v[156:159], v[196:199], v[84:87]
	v_mfma_f32_16x16x32_bf16 v[72:75], v[148:151], v[204:207], v[72:75]
	v_mfma_f32_16x16x32_bf16 v[68:71], v[156:159], v[204:207], v[68:71]
	v_mfma_f32_16x16x32_bf16 v[120:123], v[152:155], v[178:181], v[120:123]
	v_mfma_f32_16x16x32_bf16 v[116:119], v[170:173], v[178:181], v[116:119]
	v_mfma_f32_16x16x32_bf16 v[104:107], v[152:155], v[192:195], v[104:107]
	v_mfma_f32_16x16x32_bf16 v[100:103], v[170:173], v[192:195], v[100:103]
	v_mfma_f32_16x16x32_bf16 v[88:91], v[152:155], v[200:203], v[88:91]
	v_mfma_f32_16x16x32_bf16 v[84:87], v[170:173], v[200:203], v[84:87]
	v_mfma_f32_16x16x32_bf16 v[72:75], v[152:155], v[208:211], v[72:75]
	v_mfma_f32_16x16x32_bf16 v[68:71], v[170:173], v[208:211], v[68:71]
	s_barrier
	s_setprio 0
	s_add_i32 s22, s67, s30
	v_lshl_add_u64 v[212:213], v[212:213], 0, s[70:71]
	s_mov_b32 m0, s22
	ds_read_b128 v[174:177], v186 offset:49152
	ds_read_b128 v[178:181], v186 offset:50176
	ds_read_b128 v[188:191], v186 offset:51200
	ds_read_b128 v[192:195], v186 offset:52224
	ds_read_b128 v[196:199], v186 offset:53248
	ds_read_b128 v[200:203], v186 offset:54272
	ds_read_b128 v[204:207], v186 offset:55296
	ds_read_b128 v[208:211], v186 offset:56320
	global_load_lds_dwordx4 v[212:213], off
	s_add_i32 m0, s22, 0x2000
	s_add_u32 s22, s26, 0x160080
	v_lshl_add_u64 v[212:213], v[214:215], 0, s[70:71]
	s_addc_u32 s23, s27, 0
	s_add_i32 s26, s69, s30
	global_load_lds_dwordx4 v[212:213], off
	v_lshl_add_u64 v[212:213], s[22:23], 0, v[162:163]
	s_mov_b32 m0, s26
	s_nop 0
	global_load_lds_dwordx4 v[212:213], off
	v_lshl_add_u64 v[212:213], s[22:23], 0, v[0:1]
	s_add_i32 m0, s26, 0x2000
	s_nop 0
	global_load_lds_dwordx4 v[212:213], off
	v_lshl_add_u64 v[212:213], v[216:217], 0, s[70:71]
	s_mov_b32 m0, s38
	s_nop 0
	global_load_lds_dwordx4 v[212:213], off
	v_lshl_add_u64 v[212:213], v[226:227], 0, s[70:71]
	s_mov_b32 m0, s39
	s_nop 0
	global_load_lds_dwordx4 v[212:213], off
	s_waitcnt vmcnt(8)
	s_waitcnt lgkmcnt(0)
	s_setprio 1
	s_barrier
	v_mfma_f32_16x16x32_bf16 v[64:67], v[132:135], v[174:177], v[64:67]
	v_mfma_f32_16x16x32_bf16 v[60:63], v[140:143], v[174:177], v[60:63]
	v_mfma_f32_16x16x32_bf16 v[48:51], v[132:135], v[188:191], v[48:51]
	v_mfma_f32_16x16x32_bf16 v[44:47], v[140:143], v[188:191], v[44:47]
	v_mfma_f32_16x16x32_bf16 v[32:35], v[132:135], v[196:199], v[32:35]
	v_mfma_f32_16x16x32_bf16 v[28:31], v[140:143], v[196:199], v[28:31]
	v_mfma_f32_16x16x32_bf16 v[16:19], v[132:135], v[204:207], v[16:19]
	v_mfma_f32_16x16x32_bf16 v[12:15], v[140:143], v[204:207], v[12:15]
	v_mfma_f32_16x16x32_bf16 v[64:67], v[136:139], v[178:181], v[64:67]
	v_mfma_f32_16x16x32_bf16 v[60:63], v[144:147], v[178:181], v[60:63]
	v_mfma_f32_16x16x32_bf16 v[48:51], v[136:139], v[192:195], v[48:51]
	v_mfma_f32_16x16x32_bf16 v[44:47], v[144:147], v[192:195], v[44:47]
	v_mfma_f32_16x16x32_bf16 v[32:35], v[136:139], v[200:203], v[32:35]
	v_mfma_f32_16x16x32_bf16 v[28:31], v[144:147], v[200:203], v[28:31]
	v_mfma_f32_16x16x32_bf16 v[16:19], v[136:139], v[208:211], v[16:19]
	v_mfma_f32_16x16x32_bf16 v[12:15], v[144:147], v[208:211], v[12:15]
	s_setprio 0
	s_setprio 1
	v_mfma_f32_16x16x32_bf16 v[56:59], v[148:151], v[174:177], v[56:59]
	v_mfma_f32_16x16x32_bf16 v[52:55], v[156:159], v[174:177], v[52:55]
	v_mfma_f32_16x16x32_bf16 v[40:43], v[148:151], v[188:191], v[40:43]
	v_mfma_f32_16x16x32_bf16 v[36:39], v[156:159], v[188:191], v[36:39]
	v_mfma_f32_16x16x32_bf16 v[24:27], v[148:151], v[196:199], v[24:27]
	v_mfma_f32_16x16x32_bf16 v[20:23], v[156:159], v[196:199], v[20:23]
	v_mfma_f32_16x16x32_bf16 v[8:11], v[148:151], v[204:207], v[8:11]
	v_mfma_f32_16x16x32_bf16 v[4:7], v[156:159], v[204:207], v[4:7]
	v_mfma_f32_16x16x32_bf16 v[56:59], v[152:155], v[178:181], v[56:59]
	v_mfma_f32_16x16x32_bf16 v[52:55], v[170:173], v[178:181], v[52:55]
	v_mfma_f32_16x16x32_bf16 v[40:43], v[152:155], v[192:195], v[40:43]
	v_mfma_f32_16x16x32_bf16 v[36:39], v[170:173], v[192:195], v[36:39]
	v_mfma_f32_16x16x32_bf16 v[24:27], v[152:155], v[200:203], v[24:27]
	v_mfma_f32_16x16x32_bf16 v[20:23], v[170:173], v[200:203], v[20:23]
	v_mfma_f32_16x16x32_bf16 v[8:11], v[152:155], v[208:211], v[8:11]
	v_mfma_f32_16x16x32_bf16 v[4:7], v[170:173], v[208:211], v[4:7]
	s_barrier
	s_setprio 0
	s_add_i32 s66, s66, 2
	s_add_u32 s52, s52, 0x100
	s_addc_u32 s54, s54, 0
	s_cmpk_gt_u32 s66, 0x55
	s_mov_b64 s[22:23], s[24:25]
	s_cbranch_scc0 .LBB0_1205
	s_and_b64 vcc, exec, s[18:19]
	s_cbranch_vccz .LBB0_1208
	s_barrier
